# nt (non-temporal) hint on the SwiGLU epilogue h stores, to keep streamed GEMM operands in L2
# baseline (speedup 1.0000x reference)
; __device__ __forceinline__ unsigned cvtpk(float lo, float hi) { f32x2v_ v = {lo, hi}; bf16x2v_ b = __builtin_convertvector(v, bf16x2v_); return __builtin_bit_cast(unsigned, b); }
; __device__ __forceinline__ float row_rs(const float* ssp, int row) { const unsigned long long v = ((const unsigned long long*)ssp)[row];
;     return __builtin_amdgcn_rsqf((float)v * (1.0f / 4294967296.0f) * (1.0f / 1024.0f) + RMS_EPS); }
;     __device__ __forceinline__ void operator()(const f32x4 (&acc)[2][2][4][2], const Unit& u, int wr, int wc, int fr, int fq) const {
;         const int row0 = u.pm * BM + wr * 64 + fr, col0 = u.pn * HALF + wc * 32 + 8 * fq;
; #pragma unroll
;         for (int ai = 0; ai < 2; ++ai)
; #pragma unroll
;             for (int m = 0; m < 4; ++m) { const int row = row0 + ai * HALF + m * 16; const float rs = row_rs(ss, row);
;                 float hv[8];
; #pragma unroll
;                 for (int n = 0; n < 2; ++n)
; #pragma unroll
;                     for (int i = 0; i < 4; ++i) { const float g = acc[ai][0][m][n][i] * rs, uu = acc[ai][1][m][n][i] * rs;
;                         hv[n * 4 + i] = g * __builtin_amdgcn_rcpf(1.0f + __expf(-g)) * uu; }
;                 u32x4 w; w.x = cvtpk(hv[0], hv[1]); w.y = cvtpk(hv[2], hv[3]); w.z = cvtpk(hv[4], hv[5]); w.w = cvtpk(hv[6], hv[7]);
;                 *(u32x4*)(H + (size_t)row * ldh + col0) = w; }
.LBB0_194:
	v_lshl_or_b32 v160, s66, 7, v154
	v_ashrrev_i32_e32 v161, 31, v160
	v_or_b32_e32 v164, 16, v144
	v_ashrrev_i32_e32 v165, 31, v164
	v_lshl_add_u64 v[168:169], v[164:165], 3, s[6:7]
	v_mov_b64_e32 v[146:147], s[20:21]
	v_mad_i64_i32 v[162:163], s[14:15], v144, s65, v[146:147]
	s_andn2_b64 vcc, exec, s[0:1]
	s_mov_b64 s[0:1], -1
	s_waitcnt vmcnt(7)
	v_cvt_f32_u32_e32 v159, v183
	v_cvt_f32_u32_e32 v145, v182
	v_lshlrev_b64 v[148:149], 1, v[160:161]
	v_lshl_add_u64 v[162:163], v[162:163], 0, v[148:149]
	v_fmamk_f32 v145, v145, 0x2f800000, v159
	v_fmamk_f32 v145, v145, 0x3a800000, v158
	v_rsq_f32_e32 v160, v145
	s_nop 0
	v_mul_f32_e32 v182, 0xbfb8aa3b, v160
	v_mul_f32_e32 v183, v160, v160
	v_pk_mul_f32 v[160:161], v[124:125], v[182:183] op_sel_hi:[1,0]
	v_pk_mul_f32 v[170:171], v[126:127], v[182:183] op_sel_hi:[1,0]
	v_pk_mul_f32 v[172:173], v[120:121], v[182:183] op_sel_hi:[1,0]
	v_pk_mul_f32 v[174:175], v[122:123], v[182:183] op_sel_hi:[1,0]
	v_pk_mul_f32 v[116:117], v[116:117], v[124:125]
	v_pk_mul_f32 v[118:119], v[118:119], v[126:127]
	v_pk_mul_f32 v[120:121], v[112:113], v[120:121]
	v_pk_mul_f32 v[122:123], v[114:115], v[122:123]
	v_exp_f32_e32 v160, v160
	v_exp_f32_e32 v161, v161
	v_exp_f32_e32 v170, v170
	v_exp_f32_e32 v171, v171
	v_exp_f32_e32 v172, v172
	v_exp_f32_e32 v173, v173
	v_exp_f32_e32 v174, v174
	v_exp_f32_e32 v175, v175
	v_pk_mul_f32 v[116:117], v[116:117], v[182:183] op_sel:[0,1] op_sel_hi:[1,1]
	v_pk_mul_f32 v[118:119], v[118:119], v[182:183] op_sel:[0,1] op_sel_hi:[1,1]
	v_pk_mul_f32 v[120:121], v[120:121], v[182:183] op_sel:[0,1] op_sel_hi:[1,1]
	v_pk_mul_f32 v[122:123], v[122:123], v[182:183] op_sel:[0,1] op_sel_hi:[1,1]
	v_pk_add_f32 v[160:161], v[160:161], 1.0 op_sel_hi:[1,0]
	v_pk_add_f32 v[170:171], v[170:171], 1.0 op_sel_hi:[1,0]
	v_pk_add_f32 v[172:173], v[172:173], 1.0 op_sel_hi:[1,0]
	v_pk_add_f32 v[174:175], v[174:175], 1.0 op_sel_hi:[1,0]
	v_rcp_f32_e32 v160, v160
	v_rcp_f32_e32 v161, v161
	v_rcp_f32_e32 v170, v170
	v_rcp_f32_e32 v171, v171
	v_rcp_f32_e32 v172, v172
	v_rcp_f32_e32 v173, v173
	v_rcp_f32_e32 v174, v174
	v_rcp_f32_e32 v175, v175
	v_pk_mul_f32 v[116:117], v[116:117], v[160:161]
	v_pk_mul_f32 v[118:119], v[118:119], v[170:171]
	v_pk_mul_f32 v[120:121], v[120:121], v[172:173]
	v_pk_mul_f32 v[122:123], v[122:123], v[174:175]
	v_cvt_pk_bf16_f32 v112, v116, v117
	v_cvt_pk_bf16_f32 v113, v118, v119
	v_cvt_pk_bf16_f32 v114, v120, v121
	v_cvt_pk_bf16_f32 v115, v122, v123
	global_store_dwordx4 v[162:163], v[112:115], off nt
	s_nop 0
	s_nop 0
	v_or_b32_e32 v114, 32, v144
	s_waitcnt vmcnt(7)
	v_cvt_f32_u32_e32 v116, v185
	v_cvt_f32_u32_e32 v115, v184
	v_mad_i64_i32 v[112:113], s[14:15], v164, s65, v[146:147]
	v_fmamk_f32 v115, v115, 0x2f800000, v116
	v_fmamk_f32 v115, v115, 0x3a800000, v158
	v_rsq_f32_e32 v116, v115
	v_ashrrev_i32_e32 v115, 31, v114
	v_lshl_add_u64 v[118:119], v[114:115], 3, s[6:7]
	v_lshl_add_u64 v[112:113], v[112:113], 0, v[148:149]
	v_mul_f32_e32 v184, 0xbfb8aa3b, v116
	v_mul_f32_e32 v185, v116, v116
	v_pk_mul_f32 v[116:117], v[108:109], v[184:185] op_sel_hi:[1,0]
	v_pk_mul_f32 v[120:121], v[110:111], v[184:185] op_sel_hi:[1,0]
	v_pk_mul_f32 v[122:123], v[104:105], v[184:185] op_sel_hi:[1,0]
	v_pk_mul_f32 v[124:125], v[106:107], v[184:185] op_sel_hi:[1,0]
	v_pk_mul_f32 v[100:101], v[100:101], v[108:109]
	v_pk_mul_f32 v[102:103], v[102:103], v[110:111]
	v_pk_mul_f32 v[104:105], v[96:97], v[104:105]
	v_pk_mul_f32 v[106:107], v[98:99], v[106:107]
	v_exp_f32_e32 v116, v116
	v_exp_f32_e32 v117, v117
	v_exp_f32_e32 v120, v120
	v_exp_f32_e32 v121, v121
	v_exp_f32_e32 v122, v122
	v_exp_f32_e32 v123, v123
	v_exp_f32_e32 v124, v124
	v_exp_f32_e32 v125, v125
	v_pk_mul_f32 v[100:101], v[100:101], v[184:185] op_sel:[0,1] op_sel_hi:[1,1]
	v_pk_mul_f32 v[102:103], v[102:103], v[184:185] op_sel:[0,1] op_sel_hi:[1,1]
	v_pk_mul_f32 v[104:105], v[104:105], v[184:185] op_sel:[0,1] op_sel_hi:[1,1]
	v_pk_mul_f32 v[106:107], v[106:107], v[184:185] op_sel:[0,1] op_sel_hi:[1,1]
	v_pk_add_f32 v[116:117], v[116:117], 1.0 op_sel_hi:[1,0]
	v_pk_add_f32 v[120:121], v[120:121], 1.0 op_sel_hi:[1,0]
	v_pk_add_f32 v[122:123], v[122:123], 1.0 op_sel_hi:[1,0]
	v_pk_add_f32 v[124:125], v[124:125], 1.0 op_sel_hi:[1,0]
	v_rcp_f32_e32 v116, v116
	v_rcp_f32_e32 v117, v117
	v_rcp_f32_e32 v120, v120
	v_rcp_f32_e32 v121, v121
	v_rcp_f32_e32 v122, v122
	v_rcp_f32_e32 v123, v123
	v_rcp_f32_e32 v124, v124
	v_rcp_f32_e32 v125, v125
	v_pk_mul_f32 v[100:101], v[100:101], v[116:117]
	v_pk_mul_f32 v[102:103], v[102:103], v[120:121]
	v_pk_mul_f32 v[104:105], v[104:105], v[122:123]
	v_pk_mul_f32 v[106:107], v[106:107], v[124:125]
	v_cvt_pk_bf16_f32 v96, v100, v101
	v_cvt_pk_bf16_f32 v97, v102, v103
	v_cvt_pk_bf16_f32 v98, v104, v105
	v_cvt_pk_bf16_f32 v99, v106, v107
	global_store_dwordx4 v[112:113], v[96:99], off nt
	s_nop 0
	s_nop 0
	v_or_b32_e32 v98, 48, v144
	s_waitcnt vmcnt(7)
; __device__ __forceinline__ unsigned cvtpk(float lo, float hi) { f32x2v_ v = {lo, hi}; bf16x2v_ b = __builtin_convertvector(v, bf16x2v_); return __builtin_bit_cast(unsigned, b); }
; __device__ __forceinline__ float row_rs(const float* ssp, int row) { const unsigned long long v = ((const unsigned long long*)ssp)[row];
;     return __builtin_amdgcn_rsqf((float)v * (1.0f / 4294967296.0f) * (1.0f / 1024.0f) + RMS_EPS); }
;     __device__ __forceinline__ void operator()(const f32x4 (&acc)[2][2][4][2], const Unit& u, int wr, int wc, int fr, int fq) const {
;     ...
;             for (int m = 0; m < 4; ++m) { const int row = row0 + ai * HALF + m * 16; const float rs = row_rs(ss, row);
;                 float hv[8];
; #pragma unroll
;                 for (int n = 0; n < 2; ++n)
; #pragma unroll
;                     for (int i = 0; i < 4; ++i) { const float g = acc[ai][0][m][n][i] * rs, uu = acc[ai][1][m][n][i] * rs;
;                         hv[n * 4 + i] = g * __builtin_amdgcn_rcpf(1.0f + __expf(-g)) * uu; }
;                 u32x4 w; w.x = cvtpk(hv[0], hv[1]); w.y = cvtpk(hv[2], hv[3]); w.z = cvtpk(hv[4], hv[5]); w.w = cvtpk(hv[6], hv[7]);
;                 *(u32x4*)(H + (size_t)row * ldh + col0) = w; }
	v_cvt_f32_u32_e32 v100, v187
	v_cvt_f32_u32_e32 v99, v186
	v_mad_i64_i32 v[96:97], s[14:15], v114, s65, v[146:147]
	v_fmamk_f32 v99, v99, 0x2f800000, v100
	v_fmamk_f32 v99, v99, 0x3a800000, v158
	v_rsq_f32_e32 v100, v99
	v_ashrrev_i32_e32 v99, 31, v98
	v_lshl_add_u64 v[102:103], v[98:99], 3, s[6:7]
	v_lshl_add_u64 v[96:97], v[96:97], 0, v[148:149]
	v_mul_f32_e32 v186, 0xbfb8aa3b, v100
	v_mul_f32_e32 v187, v100, v100
	v_pk_mul_f32 v[100:101], v[92:93], v[186:187] op_sel_hi:[1,0]
	v_pk_mul_f32 v[104:105], v[94:95], v[186:187] op_sel_hi:[1,0]
	v_pk_mul_f32 v[106:107], v[88:89], v[186:187] op_sel_hi:[1,0]
	v_pk_mul_f32 v[108:109], v[90:91], v[186:187] op_sel_hi:[1,0]
	v_pk_mul_f32 v[84:85], v[84:85], v[92:93]
	v_pk_mul_f32 v[86:87], v[86:87], v[94:95]
	v_pk_mul_f32 v[88:89], v[80:81], v[88:89]
	v_pk_mul_f32 v[90:91], v[82:83], v[90:91]
	v_exp_f32_e32 v100, v100
	v_exp_f32_e32 v101, v101
	v_exp_f32_e32 v104, v104
	v_exp_f32_e32 v105, v105
	v_exp_f32_e32 v106, v106
	v_exp_f32_e32 v107, v107
	v_exp_f32_e32 v108, v108
	v_exp_f32_e32 v109, v109
	v_pk_mul_f32 v[84:85], v[84:85], v[186:187] op_sel:[0,1] op_sel_hi:[1,1]
	v_pk_mul_f32 v[86:87], v[86:87], v[186:187] op_sel:[0,1] op_sel_hi:[1,1]
	v_pk_mul_f32 v[88:89], v[88:89], v[186:187] op_sel:[0,1] op_sel_hi:[1,1]
	v_pk_mul_f32 v[90:91], v[90:91], v[186:187] op_sel:[0,1] op_sel_hi:[1,1]
	v_pk_add_f32 v[100:101], v[100:101], 1.0 op_sel_hi:[1,0]
	v_pk_add_f32 v[104:105], v[104:105], 1.0 op_sel_hi:[1,0]
	v_pk_add_f32 v[106:107], v[106:107], 1.0 op_sel_hi:[1,0]
	v_pk_add_f32 v[108:109], v[108:109], 1.0 op_sel_hi:[1,0]
	v_rcp_f32_e32 v100, v100
	v_rcp_f32_e32 v101, v101
	v_rcp_f32_e32 v104, v104
	v_rcp_f32_e32 v105, v105
	v_rcp_f32_e32 v106, v106
	v_rcp_f32_e32 v107, v107
	v_rcp_f32_e32 v108, v108
	v_rcp_f32_e32 v109, v109
	v_pk_mul_f32 v[84:85], v[84:85], v[100:101]
	v_pk_mul_f32 v[86:87], v[86:87], v[104:105]
	v_pk_mul_f32 v[88:89], v[88:89], v[106:107]
	v_pk_mul_f32 v[90:91], v[90:91], v[108:109]
	v_cvt_pk_bf16_f32 v80, v84, v85
	v_cvt_pk_bf16_f32 v81, v86, v87
	v_cvt_pk_bf16_f32 v82, v88, v89
	v_cvt_pk_bf16_f32 v83, v90, v91
	global_store_dwordx4 v[96:97], v[80:83], off nt
	s_nop 0
	s_waitcnt vmcnt(7)
	v_cvt_f32_u32_e32 v80, v189
	v_cvt_f32_u32_e32 v81, v188
	v_mad_i64_i32 v[82:83], s[14:15], v98, s65, v[146:147]
	v_fmamk_f32 v80, v81, 0x2f800000, v80
	v_fmamk_f32 v80, v80, 0x3a800000, v158
	v_rsq_f32_e32 v80, v80
	v_lshl_add_u64 v[82:83], v[82:83], 0, v[148:149]
	v_mul_f32_e32 v188, 0xbfb8aa3b, v80
	v_mul_f32_e32 v189, v80, v80
	v_pk_mul_f32 v[80:81], v[76:77], v[188:189] op_sel_hi:[1,0]
	v_pk_mul_f32 v[84:85], v[78:79], v[188:189] op_sel_hi:[1,0]
	v_pk_mul_f32 v[86:87], v[72:73], v[188:189] op_sel_hi:[1,0]
	v_pk_mul_f32 v[88:89], v[74:75], v[188:189] op_sel_hi:[1,0]
	v_pk_mul_f32 v[68:69], v[68:69], v[76:77]
	v_pk_mul_f32 v[70:71], v[70:71], v[78:79]
	v_pk_mul_f32 v[72:73], v[64:65], v[72:73]
	v_pk_mul_f32 v[74:75], v[66:67], v[74:75]
	v_exp_f32_e32 v80, v80
	v_exp_f32_e32 v81, v81
	v_exp_f32_e32 v84, v84
	v_exp_f32_e32 v85, v85
	v_exp_f32_e32 v86, v86
	v_exp_f32_e32 v87, v87
	v_exp_f32_e32 v88, v88
	v_exp_f32_e32 v89, v89
	v_pk_mul_f32 v[68:69], v[68:69], v[188:189] op_sel:[0,1] op_sel_hi:[1,1]
	v_pk_mul_f32 v[70:71], v[70:71], v[188:189] op_sel:[0,1] op_sel_hi:[1,1]
	v_pk_mul_f32 v[72:73], v[72:73], v[188:189] op_sel:[0,1] op_sel_hi:[1,1]
	v_pk_mul_f32 v[74:75], v[74:75], v[188:189] op_sel:[0,1] op_sel_hi:[1,1]
	v_pk_add_f32 v[80:81], v[80:81], 1.0 op_sel_hi:[1,0]
	v_pk_add_f32 v[84:85], v[84:85], 1.0 op_sel_hi:[1,0]
	v_pk_add_f32 v[86:87], v[86:87], 1.0 op_sel_hi:[1,0]
	v_pk_add_f32 v[88:89], v[88:89], 1.0 op_sel_hi:[1,0]
	v_rcp_f32_e32 v80, v80
	v_rcp_f32_e32 v81, v81
	v_rcp_f32_e32 v84, v84
	v_rcp_f32_e32 v85, v85
	v_rcp_f32_e32 v86, v86
	v_rcp_f32_e32 v87, v87
	v_rcp_f32_e32 v88, v88
	v_rcp_f32_e32 v89, v89
	v_pk_mul_f32 v[68:69], v[68:69], v[80:81]
	v_pk_mul_f32 v[70:71], v[70:71], v[84:85]
	v_pk_mul_f32 v[72:73], v[72:73], v[86:87]
	v_pk_mul_f32 v[74:75], v[74:75], v[88:89]
	v_cvt_pk_bf16_f32 v64, v68, v69
	v_cvt_pk_bf16_f32 v65, v70, v71
	v_cvt_pk_bf16_f32 v66, v72, v73
	v_cvt_pk_bf16_f32 v67, v74, v75
	global_store_dwordx4 v[82:83], v[64:67], off nt
	s_nop 0
	s_waitcnt vmcnt(7)
	v_cvt_f32_u32_e32 v64, v191
	v_cvt_f32_u32_e32 v66, v190
	v_add_u32_e32 v65, 0x80, v144
	v_fmamk_f32 v64, v66, 0x2f800000, v64
	v_fmamk_f32 v64, v64, 0x3a800000, v158
	v_rsq_f32_e32 v64, v64
	v_mad_i64_i32 v[66:67], s[14:15], v65, s65, v[146:147]
	v_lshl_add_u64 v[66:67], v[66:67], 0, v[148:149]
	v_mul_f32_e32 v190, 0xbfb8aa3b, v64
	v_mul_f32_e32 v191, v64, v64
	v_pk_mul_f32 v[64:65], v[60:61], v[190:191] op_sel_hi:[1,0]
	v_pk_mul_f32 v[68:69], v[62:63], v[190:191] op_sel_hi:[1,0]
	v_pk_mul_f32 v[70:71], v[56:57], v[190:191] op_sel_hi:[1,0]
	v_pk_mul_f32 v[72:73], v[58:59], v[190:191] op_sel_hi:[1,0]
	v_pk_mul_f32 v[52:53], v[52:53], v[60:61]
	v_pk_mul_f32 v[54:55], v[54:55], v[62:63]
	v_pk_mul_f32 v[56:57], v[48:49], v[56:57]
	v_pk_mul_f32 v[58:59], v[50:51], v[58:59]
	v_exp_f32_e32 v64, v64
	v_exp_f32_e32 v65, v65
	v_exp_f32_e32 v68, v68
	v_exp_f32_e32 v69, v69
	v_exp_f32_e32 v70, v70
	v_exp_f32_e32 v71, v71
	v_exp_f32_e32 v72, v72
	v_exp_f32_e32 v73, v73
	v_pk_mul_f32 v[52:53], v[52:53], v[190:191] op_sel:[0,1] op_sel_hi:[1,1]
	v_pk_mul_f32 v[54:55], v[54:55], v[190:191] op_sel:[0,1] op_sel_hi:[1,1]
	v_pk_mul_f32 v[56:57], v[56:57], v[190:191] op_sel:[0,1] op_sel_hi:[1,1]
	v_pk_mul_f32 v[58:59], v[58:59], v[190:191] op_sel:[0,1] op_sel_hi:[1,1]
	v_pk_add_f32 v[64:65], v[64:65], 1.0 op_sel_hi:[1,0]
	v_pk_add_f32 v[68:69], v[68:69], 1.0 op_sel_hi:[1,0]
	v_pk_add_f32 v[70:71], v[70:71], 1.0 op_sel_hi:[1,0]
	v_pk_add_f32 v[72:73], v[72:73], 1.0 op_sel_hi:[1,0]
	v_rcp_f32_e32 v64, v64
	v_rcp_f32_e32 v65, v65
	v_rcp_f32_e32 v68, v68
	v_rcp_f32_e32 v69, v69
	v_rcp_f32_e32 v70, v70
	v_rcp_f32_e32 v71, v71
	v_rcp_f32_e32 v72, v72
	v_rcp_f32_e32 v73, v73
	v_pk_mul_f32 v[52:53], v[52:53], v[64:65]
	v_pk_mul_f32 v[54:55], v[54:55], v[68:69]
	v_pk_mul_f32 v[56:57], v[56:57], v[70:71]
	v_pk_mul_f32 v[58:59], v[58:59], v[72:73]
	v_cvt_pk_bf16_f32 v48, v52, v53
	v_cvt_pk_bf16_f32 v49, v54, v55
	v_cvt_pk_bf16_f32 v50, v56, v57
	v_cvt_pk_bf16_f32 v51, v58, v59
	global_store_dwordx4 v[66:67], v[48:51], off nt
	s_nop 0
	s_waitcnt vmcnt(7)
; __device__ __forceinline__ unsigned cvtpk(float lo, float hi) { f32x2v_ v = {lo, hi}; bf16x2v_ b = __builtin_convertvector(v, bf16x2v_); return __builtin_bit_cast(unsigned, b); }
; #define PG8_BAR __builtin_amdgcn_s_barrier()
;     __device__ __forceinline__ void operator()(const f32x4 (&acc)[2][2][4][2], const Unit& u, int wr, int wc, int fr, int fq) const {
;     ...
;             for (int m = 0; m < 4; ++m) { const int row = row0 + ai * HALF + m * 16; const float rs = row_rs(ss, row);
;                 float hv[8];
; #pragma unroll
;                 for (int n = 0; n < 2; ++n)
; #pragma unroll
;                     for (int i = 0; i < 4; ++i) { const float g = acc[ai][0][m][n][i] * rs, uu = acc[ai][1][m][n][i] * rs;
;                         hv[n * 4 + i] = g * __builtin_amdgcn_rcpf(1.0f + __expf(-g)) * uu; }
;                 u32x4 w; w.x = cvtpk(hv[0], hv[1]); w.y = cvtpk(hv[2], hv[3]); w.z = cvtpk(hv[4], hv[5]); w.w = cvtpk(hv[6], hv[7]);
;                 *(u32x4*)(H + (size_t)row * ldh + col0) = w; }
; template <class Epi, class Sched, bool ALIGN_EPI = false, bool SP2 = false>
; __device__ __forceinline__ void gemm_phase(PG8_LAS unsigned char* lds, const Gemm g, const Sched& S, const Epi& E) {
;     ...
;         if (!has_next) break;
; #pragma unroll
;         for (int a = 0; a < 2; ++a)
; #pragma unroll
;             for (int b = 0; b < 2; ++b)
; #pragma unroll
;                 for (int m = 0; m < 4; ++m)
; #pragma unroll
;                     for (int n = 0; n < 2; ++n) acc[a][b][m][n] = (f32x4){0.f, 0.f, 0.f, 0.f};
;         cur = nxt; cA = nA; cB = nB; ++ui;
;         if constexpr (ALIGN_EPI) { if (wr == 1) PG8_BAR; }
	v_cvt_f32_u32_e32 v48, v193
	v_cvt_f32_u32_e32 v50, v192
	v_add_u32_e32 v49, 0x90, v144
	v_fmamk_f32 v48, v50, 0x2f800000, v48
	v_fmamk_f32 v48, v48, 0x3a800000, v158
	v_rsq_f32_e32 v48, v48
	v_mad_i64_i32 v[50:51], s[14:15], v49, s65, v[146:147]
	v_lshl_add_u64 v[50:51], v[50:51], 0, v[148:149]
	v_mul_f32_e32 v192, 0xbfb8aa3b, v48
	v_mul_f32_e32 v193, v48, v48
	v_pk_mul_f32 v[48:49], v[44:45], v[192:193] op_sel_hi:[1,0]
	v_pk_mul_f32 v[52:53], v[46:47], v[192:193] op_sel_hi:[1,0]
	v_pk_mul_f32 v[54:55], v[40:41], v[192:193] op_sel_hi:[1,0]
	v_pk_mul_f32 v[56:57], v[42:43], v[192:193] op_sel_hi:[1,0]
	v_pk_mul_f32 v[36:37], v[36:37], v[44:45]
	v_pk_mul_f32 v[38:39], v[38:39], v[46:47]
	v_pk_mul_f32 v[40:41], v[32:33], v[40:41]
	v_pk_mul_f32 v[42:43], v[34:35], v[42:43]
	v_exp_f32_e32 v48, v48
	v_exp_f32_e32 v49, v49
	v_exp_f32_e32 v52, v52
	v_exp_f32_e32 v53, v53
	v_exp_f32_e32 v54, v54
	v_exp_f32_e32 v55, v55
	v_exp_f32_e32 v56, v56
	v_exp_f32_e32 v57, v57
	v_pk_mul_f32 v[36:37], v[36:37], v[192:193] op_sel:[0,1] op_sel_hi:[1,1]
	v_pk_mul_f32 v[38:39], v[38:39], v[192:193] op_sel:[0,1] op_sel_hi:[1,1]
	v_pk_mul_f32 v[40:41], v[40:41], v[192:193] op_sel:[0,1] op_sel_hi:[1,1]
	v_pk_mul_f32 v[42:43], v[42:43], v[192:193] op_sel:[0,1] op_sel_hi:[1,1]
	v_pk_add_f32 v[48:49], v[48:49], 1.0 op_sel_hi:[1,0]
	v_pk_add_f32 v[52:53], v[52:53], 1.0 op_sel_hi:[1,0]
	v_pk_add_f32 v[54:55], v[54:55], 1.0 op_sel_hi:[1,0]
	v_pk_add_f32 v[56:57], v[56:57], 1.0 op_sel_hi:[1,0]
	v_rcp_f32_e32 v48, v48
	v_rcp_f32_e32 v49, v49
	v_rcp_f32_e32 v52, v52
	v_rcp_f32_e32 v53, v53
	v_rcp_f32_e32 v54, v54
	v_rcp_f32_e32 v55, v55
	v_rcp_f32_e32 v56, v56
	v_rcp_f32_e32 v57, v57
	v_pk_mul_f32 v[36:37], v[36:37], v[48:49]
	v_pk_mul_f32 v[38:39], v[38:39], v[52:53]
	v_pk_mul_f32 v[40:41], v[40:41], v[54:55]
	v_pk_mul_f32 v[42:43], v[42:43], v[56:57]
	v_cvt_pk_bf16_f32 v32, v36, v37
	v_cvt_pk_bf16_f32 v33, v38, v39
	v_cvt_pk_bf16_f32 v34, v40, v41
	v_cvt_pk_bf16_f32 v35, v42, v43
	global_store_dwordx4 v[50:51], v[32:35], off nt
	s_nop 0
	s_waitcnt vmcnt(7)
	v_cvt_f32_u32_e32 v32, v195
	v_cvt_f32_u32_e32 v34, v194
	v_add_u32_e32 v33, 0xa0, v144
	v_fmamk_f32 v32, v34, 0x2f800000, v32
	v_fmamk_f32 v32, v32, 0x3a800000, v158
	v_rsq_f32_e32 v32, v32
	v_mad_i64_i32 v[34:35], s[14:15], v33, s65, v[146:147]
	v_lshl_add_u64 v[34:35], v[34:35], 0, v[148:149]
	v_mul_f32_e32 v194, 0xbfb8aa3b, v32
	v_mul_f32_e32 v195, v32, v32
	v_pk_mul_f32 v[32:33], v[28:29], v[194:195] op_sel_hi:[1,0]
	v_pk_mul_f32 v[36:37], v[30:31], v[194:195] op_sel_hi:[1,0]
	v_pk_mul_f32 v[38:39], v[24:25], v[194:195] op_sel_hi:[1,0]
	v_pk_mul_f32 v[40:41], v[26:27], v[194:195] op_sel_hi:[1,0]
	v_pk_mul_f32 v[20:21], v[20:21], v[28:29]
	v_pk_mul_f32 v[22:23], v[22:23], v[30:31]
	v_pk_mul_f32 v[24:25], v[16:17], v[24:25]
	v_pk_mul_f32 v[26:27], v[18:19], v[26:27]
	v_exp_f32_e32 v32, v32
	v_exp_f32_e32 v33, v33
	v_exp_f32_e32 v36, v36
	v_exp_f32_e32 v37, v37
	v_exp_f32_e32 v38, v38
	v_exp_f32_e32 v39, v39
	v_exp_f32_e32 v40, v40
	v_exp_f32_e32 v41, v41
	v_pk_mul_f32 v[20:21], v[20:21], v[194:195] op_sel:[0,1] op_sel_hi:[1,1]
	v_pk_mul_f32 v[22:23], v[22:23], v[194:195] op_sel:[0,1] op_sel_hi:[1,1]
	v_pk_mul_f32 v[24:25], v[24:25], v[194:195] op_sel:[0,1] op_sel_hi:[1,1]
	v_pk_mul_f32 v[26:27], v[26:27], v[194:195] op_sel:[0,1] op_sel_hi:[1,1]
	v_pk_add_f32 v[32:33], v[32:33], 1.0 op_sel_hi:[1,0]
	v_pk_add_f32 v[36:37], v[36:37], 1.0 op_sel_hi:[1,0]
	v_pk_add_f32 v[38:39], v[38:39], 1.0 op_sel_hi:[1,0]
	v_pk_add_f32 v[40:41], v[40:41], 1.0 op_sel_hi:[1,0]
	v_rcp_f32_e32 v32, v32
	v_rcp_f32_e32 v33, v33
	v_rcp_f32_e32 v36, v36
	v_rcp_f32_e32 v37, v37
	v_rcp_f32_e32 v38, v38
	v_rcp_f32_e32 v39, v39
	v_rcp_f32_e32 v40, v40
	v_rcp_f32_e32 v41, v41
	v_pk_mul_f32 v[20:21], v[20:21], v[32:33]
	v_pk_mul_f32 v[22:23], v[22:23], v[36:37]
	v_pk_mul_f32 v[24:25], v[24:25], v[38:39]
	v_pk_mul_f32 v[26:27], v[26:27], v[40:41]
	v_cvt_pk_bf16_f32 v16, v20, v21
	v_cvt_pk_bf16_f32 v17, v22, v23
	v_cvt_pk_bf16_f32 v18, v24, v25
	v_cvt_pk_bf16_f32 v19, v26, v27
	global_store_dwordx4 v[34:35], v[16:19], off nt
	s_nop 0
	s_waitcnt vmcnt(7)
	v_cvt_f32_u32_e32 v16, v197
	v_cvt_f32_u32_e32 v18, v196
	v_add_u32_e32 v17, 0xb0, v144
	v_fmamk_f32 v16, v18, 0x2f800000, v16
	v_fmamk_f32 v16, v16, 0x3a800000, v158
	v_rsq_f32_e32 v16, v16
	v_mad_i64_i32 v[18:19], s[14:15], v17, s65, v[146:147]
	v_lshl_add_u64 v[18:19], v[18:19], 0, v[148:149]
	v_mul_f32_e32 v196, 0xbfb8aa3b, v16
	v_mul_f32_e32 v197, v16, v16
	v_pk_mul_f32 v[16:17], v[12:13], v[196:197] op_sel_hi:[1,0]
	v_pk_mul_f32 v[20:21], v[14:15], v[196:197] op_sel_hi:[1,0]
	v_pk_mul_f32 v[22:23], v[8:9], v[196:197] op_sel_hi:[1,0]
	v_pk_mul_f32 v[24:25], v[10:11], v[196:197] op_sel_hi:[1,0]
	v_pk_mul_f32 v[4:5], v[4:5], v[12:13]
	v_pk_mul_f32 v[6:7], v[6:7], v[14:15]
	v_pk_mul_f32 v[8:9], v[0:1], v[8:9]
	v_pk_mul_f32 v[10:11], v[2:3], v[10:11]
	v_exp_f32_e32 v16, v16
	v_exp_f32_e32 v17, v17
	v_exp_f32_e32 v20, v20
	v_exp_f32_e32 v21, v21
	v_exp_f32_e32 v22, v22
	v_exp_f32_e32 v23, v23
	v_exp_f32_e32 v24, v24
	v_exp_f32_e32 v25, v25
	v_pk_mul_f32 v[4:5], v[4:5], v[196:197] op_sel:[0,1] op_sel_hi:[1,1]
	v_pk_mul_f32 v[6:7], v[6:7], v[196:197] op_sel:[0,1] op_sel_hi:[1,1]
	v_pk_mul_f32 v[8:9], v[8:9], v[196:197] op_sel:[0,1] op_sel_hi:[1,1]
	v_pk_mul_f32 v[10:11], v[10:11], v[196:197] op_sel:[0,1] op_sel_hi:[1,1]
	v_pk_add_f32 v[16:17], v[16:17], 1.0 op_sel_hi:[1,0]
	v_pk_add_f32 v[20:21], v[20:21], 1.0 op_sel_hi:[1,0]
	v_pk_add_f32 v[22:23], v[22:23], 1.0 op_sel_hi:[1,0]
	v_pk_add_f32 v[24:25], v[24:25], 1.0 op_sel_hi:[1,0]
	v_rcp_f32_e32 v16, v16
	v_rcp_f32_e32 v17, v17
	v_rcp_f32_e32 v20, v20
	v_rcp_f32_e32 v21, v21
	v_rcp_f32_e32 v22, v22
	v_rcp_f32_e32 v23, v23
	v_rcp_f32_e32 v24, v24
	v_rcp_f32_e32 v25, v25
	v_pk_mul_f32 v[4:5], v[4:5], v[16:17]
	v_pk_mul_f32 v[6:7], v[6:7], v[20:21]
	v_pk_mul_f32 v[8:9], v[8:9], v[22:23]
	v_pk_mul_f32 v[10:11], v[10:11], v[24:25]
	v_cvt_pk_bf16_f32 v0, v4, v5
	v_cvt_pk_bf16_f32 v1, v6, v7
	v_cvt_pk_bf16_f32 v2, v8, v9
	v_cvt_pk_bf16_f32 v3, v10, v11
	global_store_dwordx4 v[18:19], v[0:3], off nt
	s_cbranch_vccnz .LBB0_187
	s_andn2_b64 vcc, exec, s[8:9]
	s_cbranch_vccnz .LBB0_186
	s_barrier
	s_branch .LBB0_186

; __device__ __forceinline__ unsigned cvtpk(float lo, float hi) { f32x2v_ v = {lo, hi}; bf16x2v_ b = __builtin_convertvector(v, bf16x2v_); return __builtin_bit_cast(unsigned, b); }
; __device__ __forceinline__ float row_rs(const float* ssp, int row) { const unsigned long long v = ((const unsigned long long*)ssp)[row];
;     return __builtin_amdgcn_rsqf((float)v * (1.0f / 4294967296.0f) * (1.0f / 1024.0f) + RMS_EPS); }
;     __device__ __forceinline__ void operator()(const f32x4 (&acc)[2][2][4][2], const Unit& u, int wr, int wc, int fr, int fq) const {
;         const int row0 = u.pm * BM + wr * 64 + fr, col0 = u.pn * HALF + wc * 32 + 8 * fq;
; #pragma unroll
;         for (int ai = 0; ai < 2; ++ai)
; #pragma unroll
;             for (int m = 0; m < 4; ++m) { const int row = row0 + ai * HALF + m * 16; const float rs = row_rs(ss, row);
;                 float hv[8];
; #pragma unroll
;                 for (int n = 0; n < 2; ++n)
; #pragma unroll
;                     for (int i = 0; i < 4; ++i) { const float g = acc[ai][0][m][n][i] * rs, uu = acc[ai][1][m][n][i] * rs;
;                         hv[n * 4 + i] = g * __builtin_amdgcn_rcpf(1.0f + __expf(-g)) * uu; }
;                 u32x4 w; w.x = cvtpk(hv[0], hv[1]); w.y = cvtpk(hv[2], hv[3]); w.z = cvtpk(hv[4], hv[5]); w.w = cvtpk(hv[6], hv[7]);
;                 *(u32x4*)(H + (size_t)row * ldh + col0) = w; }
.LBB0_960:
	v_lshl_or_b32 v160, s74, 7, v154
	v_ashrrev_i32_e32 v161, 31, v160
	v_or_b32_e32 v164, 16, v144
	v_ashrrev_i32_e32 v165, 31, v164
	v_lshl_add_u64 v[166:167], v[164:165], 3, s[0:1]
	v_mov_b64_e32 v[146:147], s[20:21]
	v_mad_i64_i32 v[162:163], s[54:55], v144, s67, v[146:147]
	s_andn2_b64 vcc, exec, s[10:11]
	s_mov_b64 s[10:11], -1
	s_waitcnt vmcnt(7)
	v_cvt_f32_u32_e32 v159, v183
	v_cvt_f32_u32_e32 v145, v182
	v_lshlrev_b64 v[148:149], 1, v[160:161]
	v_lshl_add_u64 v[162:163], v[162:163], 0, v[148:149]
	v_fmamk_f32 v145, v145, 0x2f800000, v159
	v_fmamk_f32 v145, v145, 0x3a800000, v158
	v_rsq_f32_e32 v160, v145
	s_nop 0
	v_mul_f32_e32 v182, 0xbfb8aa3b, v160
	v_mul_f32_e32 v183, v160, v160
	v_pk_mul_f32 v[160:161], v[124:125], v[182:183] op_sel_hi:[1,0]
	v_pk_mul_f32 v[168:169], v[126:127], v[182:183] op_sel_hi:[1,0]
	v_pk_mul_f32 v[170:171], v[120:121], v[182:183] op_sel_hi:[1,0]
	v_pk_mul_f32 v[172:173], v[122:123], v[182:183] op_sel_hi:[1,0]
	v_pk_mul_f32 v[116:117], v[116:117], v[124:125]
	v_pk_mul_f32 v[118:119], v[118:119], v[126:127]
	v_pk_mul_f32 v[120:121], v[112:113], v[120:121]
	v_pk_mul_f32 v[122:123], v[114:115], v[122:123]
	v_exp_f32_e32 v160, v160
	v_exp_f32_e32 v161, v161
	v_exp_f32_e32 v168, v168
	v_exp_f32_e32 v169, v169
	v_exp_f32_e32 v170, v170
	v_exp_f32_e32 v171, v171
	v_exp_f32_e32 v172, v172
	v_exp_f32_e32 v173, v173
	v_pk_mul_f32 v[116:117], v[116:117], v[182:183] op_sel:[0,1] op_sel_hi:[1,1]
	v_pk_mul_f32 v[118:119], v[118:119], v[182:183] op_sel:[0,1] op_sel_hi:[1,1]
	v_pk_mul_f32 v[120:121], v[120:121], v[182:183] op_sel:[0,1] op_sel_hi:[1,1]
	v_pk_mul_f32 v[122:123], v[122:123], v[182:183] op_sel:[0,1] op_sel_hi:[1,1]
	v_pk_add_f32 v[160:161], v[160:161], 1.0 op_sel_hi:[1,0]
	v_pk_add_f32 v[168:169], v[168:169], 1.0 op_sel_hi:[1,0]
	v_pk_add_f32 v[170:171], v[170:171], 1.0 op_sel_hi:[1,0]
	v_pk_add_f32 v[172:173], v[172:173], 1.0 op_sel_hi:[1,0]
	v_rcp_f32_e32 v160, v160
	v_rcp_f32_e32 v161, v161
	v_rcp_f32_e32 v168, v168
	v_rcp_f32_e32 v169, v169
	v_rcp_f32_e32 v170, v170
	v_rcp_f32_e32 v171, v171
	v_rcp_f32_e32 v172, v172
	v_rcp_f32_e32 v173, v173
	v_pk_mul_f32 v[116:117], v[116:117], v[160:161]
	v_pk_mul_f32 v[118:119], v[118:119], v[168:169]
	v_pk_mul_f32 v[120:121], v[120:121], v[170:171]
	v_pk_mul_f32 v[122:123], v[122:123], v[172:173]
	v_cvt_pk_bf16_f32 v112, v116, v117
	v_cvt_pk_bf16_f32 v113, v118, v119
	v_cvt_pk_bf16_f32 v114, v120, v121
	v_cvt_pk_bf16_f32 v115, v122, v123
	global_store_dwordx4 v[162:163], v[112:115], off nt
	s_nop 0
	s_nop 0
	v_or_b32_e32 v114, 32, v144
	s_waitcnt vmcnt(7)
	v_cvt_f32_u32_e32 v116, v185
	v_cvt_f32_u32_e32 v115, v184
	v_mad_i64_i32 v[112:113], s[54:55], v164, s67, v[146:147]
	v_fmamk_f32 v115, v115, 0x2f800000, v116
	v_fmamk_f32 v115, v115, 0x3a800000, v158
	v_rsq_f32_e32 v116, v115
	v_ashrrev_i32_e32 v115, 31, v114
	v_lshl_add_u64 v[118:119], v[114:115], 3, s[0:1]
	v_lshl_add_u64 v[112:113], v[112:113], 0, v[148:149]
	v_mul_f32_e32 v184, 0xbfb8aa3b, v116
	v_mul_f32_e32 v185, v116, v116
	v_pk_mul_f32 v[116:117], v[108:109], v[184:185] op_sel_hi:[1,0]
	v_pk_mul_f32 v[120:121], v[110:111], v[184:185] op_sel_hi:[1,0]
	v_pk_mul_f32 v[122:123], v[104:105], v[184:185] op_sel_hi:[1,0]
	v_pk_mul_f32 v[124:125], v[106:107], v[184:185] op_sel_hi:[1,0]
	v_pk_mul_f32 v[100:101], v[100:101], v[108:109]
	v_pk_mul_f32 v[102:103], v[102:103], v[110:111]
	v_pk_mul_f32 v[104:105], v[96:97], v[104:105]
	v_pk_mul_f32 v[106:107], v[98:99], v[106:107]
	v_exp_f32_e32 v116, v116
	v_exp_f32_e32 v117, v117
	v_exp_f32_e32 v120, v120
	v_exp_f32_e32 v121, v121
	v_exp_f32_e32 v122, v122
	v_exp_f32_e32 v123, v123
	v_exp_f32_e32 v124, v124
	v_exp_f32_e32 v125, v125
	v_pk_mul_f32 v[100:101], v[100:101], v[184:185] op_sel:[0,1] op_sel_hi:[1,1]
	v_pk_mul_f32 v[102:103], v[102:103], v[184:185] op_sel:[0,1] op_sel_hi:[1,1]
	v_pk_mul_f32 v[104:105], v[104:105], v[184:185] op_sel:[0,1] op_sel_hi:[1,1]
	v_pk_mul_f32 v[106:107], v[106:107], v[184:185] op_sel:[0,1] op_sel_hi:[1,1]
	v_pk_add_f32 v[116:117], v[116:117], 1.0 op_sel_hi:[1,0]
	v_pk_add_f32 v[120:121], v[120:121], 1.0 op_sel_hi:[1,0]
	v_pk_add_f32 v[122:123], v[122:123], 1.0 op_sel_hi:[1,0]
	v_pk_add_f32 v[124:125], v[124:125], 1.0 op_sel_hi:[1,0]
	v_rcp_f32_e32 v116, v116
	v_rcp_f32_e32 v117, v117
	v_rcp_f32_e32 v120, v120
	v_rcp_f32_e32 v121, v121
	v_rcp_f32_e32 v122, v122
	v_rcp_f32_e32 v123, v123
	v_rcp_f32_e32 v124, v124
	v_rcp_f32_e32 v125, v125
	v_pk_mul_f32 v[100:101], v[100:101], v[116:117]
	v_pk_mul_f32 v[102:103], v[102:103], v[120:121]
	v_pk_mul_f32 v[104:105], v[104:105], v[122:123]
	v_pk_mul_f32 v[106:107], v[106:107], v[124:125]
	v_cvt_pk_bf16_f32 v96, v100, v101
	v_cvt_pk_bf16_f32 v97, v102, v103
	v_cvt_pk_bf16_f32 v98, v104, v105
	v_cvt_pk_bf16_f32 v99, v106, v107
	global_store_dwordx4 v[112:113], v[96:99], off nt
	s_nop 0
	s_nop 0
	v_or_b32_e32 v98, 48, v144
	s_waitcnt vmcnt(7)
; __device__ __forceinline__ unsigned cvtpk(float lo, float hi) { f32x2v_ v = {lo, hi}; bf16x2v_ b = __builtin_convertvector(v, bf16x2v_); return __builtin_bit_cast(unsigned, b); }
; __device__ __forceinline__ float row_rs(const float* ssp, int row) { const unsigned long long v = ((const unsigned long long*)ssp)[row];
;     return __builtin_amdgcn_rsqf((float)v * (1.0f / 4294967296.0f) * (1.0f / 1024.0f) + RMS_EPS); }
;     __device__ __forceinline__ void operator()(const f32x4 (&acc)[2][2][4][2], const Unit& u, int wr, int wc, int fr, int fq) const {
;     ...
;             for (int m = 0; m < 4; ++m) { const int row = row0 + ai * HALF + m * 16; const float rs = row_rs(ss, row);
;                 float hv[8];
; #pragma unroll
;                 for (int n = 0; n < 2; ++n)
; #pragma unroll
;                     for (int i = 0; i < 4; ++i) { const float g = acc[ai][0][m][n][i] * rs, uu = acc[ai][1][m][n][i] * rs;
;                         hv[n * 4 + i] = g * __builtin_amdgcn_rcpf(1.0f + __expf(-g)) * uu; }
;                 u32x4 w; w.x = cvtpk(hv[0], hv[1]); w.y = cvtpk(hv[2], hv[3]); w.z = cvtpk(hv[4], hv[5]); w.w = cvtpk(hv[6], hv[7]);
;                 *(u32x4*)(H + (size_t)row * ldh + col0) = w; }
	v_cvt_f32_u32_e32 v100, v187
	v_cvt_f32_u32_e32 v99, v186
	v_mad_i64_i32 v[96:97], s[54:55], v114, s67, v[146:147]
	v_fmamk_f32 v99, v99, 0x2f800000, v100
	v_fmamk_f32 v99, v99, 0x3a800000, v158
	v_rsq_f32_e32 v100, v99
	v_ashrrev_i32_e32 v99, 31, v98
	v_lshl_add_u64 v[102:103], v[98:99], 3, s[0:1]
	v_lshl_add_u64 v[96:97], v[96:97], 0, v[148:149]
	v_mul_f32_e32 v186, 0xbfb8aa3b, v100
	v_mul_f32_e32 v187, v100, v100
	v_pk_mul_f32 v[100:101], v[92:93], v[186:187] op_sel_hi:[1,0]
	v_pk_mul_f32 v[104:105], v[94:95], v[186:187] op_sel_hi:[1,0]
	v_pk_mul_f32 v[106:107], v[88:89], v[186:187] op_sel_hi:[1,0]
	v_pk_mul_f32 v[108:109], v[90:91], v[186:187] op_sel_hi:[1,0]
	v_pk_mul_f32 v[84:85], v[84:85], v[92:93]
	v_pk_mul_f32 v[86:87], v[86:87], v[94:95]
	v_pk_mul_f32 v[88:89], v[80:81], v[88:89]
	v_pk_mul_f32 v[90:91], v[82:83], v[90:91]
	v_exp_f32_e32 v100, v100
	v_exp_f32_e32 v101, v101
	v_exp_f32_e32 v104, v104
	v_exp_f32_e32 v105, v105
	v_exp_f32_e32 v106, v106
	v_exp_f32_e32 v107, v107
	v_exp_f32_e32 v108, v108
	v_exp_f32_e32 v109, v109
	v_pk_mul_f32 v[84:85], v[84:85], v[186:187] op_sel:[0,1] op_sel_hi:[1,1]
	v_pk_mul_f32 v[86:87], v[86:87], v[186:187] op_sel:[0,1] op_sel_hi:[1,1]
	v_pk_mul_f32 v[88:89], v[88:89], v[186:187] op_sel:[0,1] op_sel_hi:[1,1]
	v_pk_mul_f32 v[90:91], v[90:91], v[186:187] op_sel:[0,1] op_sel_hi:[1,1]
	v_pk_add_f32 v[100:101], v[100:101], 1.0 op_sel_hi:[1,0]
	v_pk_add_f32 v[104:105], v[104:105], 1.0 op_sel_hi:[1,0]
	v_pk_add_f32 v[106:107], v[106:107], 1.0 op_sel_hi:[1,0]
	v_pk_add_f32 v[108:109], v[108:109], 1.0 op_sel_hi:[1,0]
	v_rcp_f32_e32 v100, v100
	v_rcp_f32_e32 v101, v101
	v_rcp_f32_e32 v104, v104
	v_rcp_f32_e32 v105, v105
	v_rcp_f32_e32 v106, v106
	v_rcp_f32_e32 v107, v107
	v_rcp_f32_e32 v108, v108
	v_rcp_f32_e32 v109, v109
	v_pk_mul_f32 v[84:85], v[84:85], v[100:101]
	v_pk_mul_f32 v[86:87], v[86:87], v[104:105]
	v_pk_mul_f32 v[88:89], v[88:89], v[106:107]
	v_pk_mul_f32 v[90:91], v[90:91], v[108:109]
	v_cvt_pk_bf16_f32 v80, v84, v85
	v_cvt_pk_bf16_f32 v81, v86, v87
	v_cvt_pk_bf16_f32 v82, v88, v89
	v_cvt_pk_bf16_f32 v83, v90, v91
	global_store_dwordx4 v[96:97], v[80:83], off nt
	s_nop 0
	s_waitcnt vmcnt(7)
	v_cvt_f32_u32_e32 v80, v189
	v_cvt_f32_u32_e32 v81, v188
	v_mad_i64_i32 v[82:83], s[54:55], v98, s67, v[146:147]
	v_fmamk_f32 v80, v81, 0x2f800000, v80
	v_fmamk_f32 v80, v80, 0x3a800000, v158
	v_rsq_f32_e32 v80, v80
	v_lshl_add_u64 v[82:83], v[82:83], 0, v[148:149]
	v_mul_f32_e32 v188, 0xbfb8aa3b, v80
	v_mul_f32_e32 v189, v80, v80
	v_pk_mul_f32 v[80:81], v[76:77], v[188:189] op_sel_hi:[1,0]
	v_pk_mul_f32 v[84:85], v[78:79], v[188:189] op_sel_hi:[1,0]
	v_pk_mul_f32 v[86:87], v[72:73], v[188:189] op_sel_hi:[1,0]
	v_pk_mul_f32 v[88:89], v[74:75], v[188:189] op_sel_hi:[1,0]
	v_pk_mul_f32 v[68:69], v[68:69], v[76:77]
	v_pk_mul_f32 v[70:71], v[70:71], v[78:79]
	v_pk_mul_f32 v[72:73], v[64:65], v[72:73]
	v_pk_mul_f32 v[74:75], v[66:67], v[74:75]
	v_exp_f32_e32 v80, v80
	v_exp_f32_e32 v81, v81
	v_exp_f32_e32 v84, v84
	v_exp_f32_e32 v85, v85
	v_exp_f32_e32 v86, v86
	v_exp_f32_e32 v87, v87
	v_exp_f32_e32 v88, v88
	v_exp_f32_e32 v89, v89
	v_pk_mul_f32 v[68:69], v[68:69], v[188:189] op_sel:[0,1] op_sel_hi:[1,1]
	v_pk_mul_f32 v[70:71], v[70:71], v[188:189] op_sel:[0,1] op_sel_hi:[1,1]
	v_pk_mul_f32 v[72:73], v[72:73], v[188:189] op_sel:[0,1] op_sel_hi:[1,1]
	v_pk_mul_f32 v[74:75], v[74:75], v[188:189] op_sel:[0,1] op_sel_hi:[1,1]
	v_pk_add_f32 v[80:81], v[80:81], 1.0 op_sel_hi:[1,0]
	v_pk_add_f32 v[84:85], v[84:85], 1.0 op_sel_hi:[1,0]
	v_pk_add_f32 v[86:87], v[86:87], 1.0 op_sel_hi:[1,0]
	v_pk_add_f32 v[88:89], v[88:89], 1.0 op_sel_hi:[1,0]
	v_rcp_f32_e32 v80, v80
	v_rcp_f32_e32 v81, v81
	v_rcp_f32_e32 v84, v84
	v_rcp_f32_e32 v85, v85
	v_rcp_f32_e32 v86, v86
	v_rcp_f32_e32 v87, v87
	v_rcp_f32_e32 v88, v88
	v_rcp_f32_e32 v89, v89
	v_pk_mul_f32 v[68:69], v[68:69], v[80:81]
	v_pk_mul_f32 v[70:71], v[70:71], v[84:85]
	v_pk_mul_f32 v[72:73], v[72:73], v[86:87]
	v_pk_mul_f32 v[74:75], v[74:75], v[88:89]
	v_cvt_pk_bf16_f32 v64, v68, v69
	v_cvt_pk_bf16_f32 v65, v70, v71
	v_cvt_pk_bf16_f32 v66, v72, v73
	v_cvt_pk_bf16_f32 v67, v74, v75
	global_store_dwordx4 v[82:83], v[64:67], off nt
	s_nop 0
	s_waitcnt vmcnt(7)
	v_cvt_f32_u32_e32 v64, v191
	v_cvt_f32_u32_e32 v66, v190
	v_add_u32_e32 v65, 0x80, v144
	v_fmamk_f32 v64, v66, 0x2f800000, v64
	v_fmamk_f32 v64, v64, 0x3a800000, v158
	v_rsq_f32_e32 v64, v64
	v_mad_i64_i32 v[66:67], s[54:55], v65, s67, v[146:147]
	v_lshl_add_u64 v[66:67], v[66:67], 0, v[148:149]
	v_mul_f32_e32 v190, 0xbfb8aa3b, v64
	v_mul_f32_e32 v191, v64, v64
	v_pk_mul_f32 v[64:65], v[60:61], v[190:191] op_sel_hi:[1,0]
	v_pk_mul_f32 v[68:69], v[62:63], v[190:191] op_sel_hi:[1,0]
	v_pk_mul_f32 v[70:71], v[56:57], v[190:191] op_sel_hi:[1,0]
	v_pk_mul_f32 v[72:73], v[58:59], v[190:191] op_sel_hi:[1,0]
	v_pk_mul_f32 v[52:53], v[52:53], v[60:61]
	v_pk_mul_f32 v[54:55], v[54:55], v[62:63]
	v_pk_mul_f32 v[56:57], v[48:49], v[56:57]
	v_pk_mul_f32 v[58:59], v[50:51], v[58:59]
	v_exp_f32_e32 v64, v64
	v_exp_f32_e32 v65, v65
	v_exp_f32_e32 v68, v68
	v_exp_f32_e32 v69, v69
	v_exp_f32_e32 v70, v70
	v_exp_f32_e32 v71, v71
	v_exp_f32_e32 v72, v72
	v_exp_f32_e32 v73, v73
	v_pk_mul_f32 v[52:53], v[52:53], v[190:191] op_sel:[0,1] op_sel_hi:[1,1]
	v_pk_mul_f32 v[54:55], v[54:55], v[190:191] op_sel:[0,1] op_sel_hi:[1,1]
	v_pk_mul_f32 v[56:57], v[56:57], v[190:191] op_sel:[0,1] op_sel_hi:[1,1]
	v_pk_mul_f32 v[58:59], v[58:59], v[190:191] op_sel:[0,1] op_sel_hi:[1,1]
	v_pk_add_f32 v[64:65], v[64:65], 1.0 op_sel_hi:[1,0]
	v_pk_add_f32 v[68:69], v[68:69], 1.0 op_sel_hi:[1,0]
	v_pk_add_f32 v[70:71], v[70:71], 1.0 op_sel_hi:[1,0]
	v_pk_add_f32 v[72:73], v[72:73], 1.0 op_sel_hi:[1,0]
	v_rcp_f32_e32 v64, v64
	v_rcp_f32_e32 v65, v65
	v_rcp_f32_e32 v68, v68
	v_rcp_f32_e32 v69, v69
	v_rcp_f32_e32 v70, v70
	v_rcp_f32_e32 v71, v71
	v_rcp_f32_e32 v72, v72
	v_rcp_f32_e32 v73, v73
	v_pk_mul_f32 v[52:53], v[52:53], v[64:65]
	v_pk_mul_f32 v[54:55], v[54:55], v[68:69]
	v_pk_mul_f32 v[56:57], v[56:57], v[70:71]
	v_pk_mul_f32 v[58:59], v[58:59], v[72:73]
	v_cvt_pk_bf16_f32 v48, v52, v53
	v_cvt_pk_bf16_f32 v49, v54, v55
	v_cvt_pk_bf16_f32 v50, v56, v57
	v_cvt_pk_bf16_f32 v51, v58, v59
	global_store_dwordx4 v[66:67], v[48:51], off nt
	s_nop 0
	s_waitcnt vmcnt(7)
; __device__ __forceinline__ unsigned cvtpk(float lo, float hi) { f32x2v_ v = {lo, hi}; bf16x2v_ b = __builtin_convertvector(v, bf16x2v_); return __builtin_bit_cast(unsigned, b); }
; #define PG8_BAR __builtin_amdgcn_s_barrier()
;     __device__ __forceinline__ void operator()(const f32x4 (&acc)[2][2][4][2], const Unit& u, int wr, int wc, int fr, int fq) const {
;     ...
;             for (int m = 0; m < 4; ++m) { const int row = row0 + ai * HALF + m * 16; const float rs = row_rs(ss, row);
;                 float hv[8];
; #pragma unroll
;                 for (int n = 0; n < 2; ++n)
; #pragma unroll
;                     for (int i = 0; i < 4; ++i) { const float g = acc[ai][0][m][n][i] * rs, uu = acc[ai][1][m][n][i] * rs;
;                         hv[n * 4 + i] = g * __builtin_amdgcn_rcpf(1.0f + __expf(-g)) * uu; }
;                 u32x4 w; w.x = cvtpk(hv[0], hv[1]); w.y = cvtpk(hv[2], hv[3]); w.z = cvtpk(hv[4], hv[5]); w.w = cvtpk(hv[6], hv[7]);
;                 *(u32x4*)(H + (size_t)row * ldh + col0) = w; }
; template <class Epi, class Sched, bool ALIGN_EPI = false, bool SP2 = false>
; __device__ __forceinline__ void gemm_phase(PG8_LAS unsigned char* lds, const Gemm g, const Sched& S, const Epi& E) {
;     ...
;         if (!has_next) break;
; #pragma unroll
;         for (int a = 0; a < 2; ++a)
; #pragma unroll
;             for (int b = 0; b < 2; ++b)
; #pragma unroll
;                 for (int m = 0; m < 4; ++m)
; #pragma unroll
;                     for (int n = 0; n < 2; ++n) acc[a][b][m][n] = (f32x4){0.f, 0.f, 0.f, 0.f};
;         cur = nxt; cA = nA; cB = nB; ++ui;
;         if constexpr (ALIGN_EPI) { if (wr == 1) PG8_BAR; }
	v_cvt_f32_u32_e32 v48, v193
	v_cvt_f32_u32_e32 v50, v192
	v_add_u32_e32 v49, 0x90, v144
	v_fmamk_f32 v48, v50, 0x2f800000, v48
	v_fmamk_f32 v48, v48, 0x3a800000, v158
	v_rsq_f32_e32 v48, v48
	v_mad_i64_i32 v[50:51], s[54:55], v49, s67, v[146:147]
	v_lshl_add_u64 v[50:51], v[50:51], 0, v[148:149]
	v_mul_f32_e32 v192, 0xbfb8aa3b, v48
	v_mul_f32_e32 v193, v48, v48
	v_pk_mul_f32 v[48:49], v[44:45], v[192:193] op_sel_hi:[1,0]
	v_pk_mul_f32 v[52:53], v[46:47], v[192:193] op_sel_hi:[1,0]
	v_pk_mul_f32 v[54:55], v[40:41], v[192:193] op_sel_hi:[1,0]
	v_pk_mul_f32 v[56:57], v[42:43], v[192:193] op_sel_hi:[1,0]
	v_pk_mul_f32 v[36:37], v[36:37], v[44:45]
	v_pk_mul_f32 v[38:39], v[38:39], v[46:47]
	v_pk_mul_f32 v[40:41], v[32:33], v[40:41]
	v_pk_mul_f32 v[42:43], v[34:35], v[42:43]
	v_exp_f32_e32 v48, v48
	v_exp_f32_e32 v49, v49
	v_exp_f32_e32 v52, v52
	v_exp_f32_e32 v53, v53
	v_exp_f32_e32 v54, v54
	v_exp_f32_e32 v55, v55
	v_exp_f32_e32 v56, v56
	v_exp_f32_e32 v57, v57
	v_pk_mul_f32 v[36:37], v[36:37], v[192:193] op_sel:[0,1] op_sel_hi:[1,1]
	v_pk_mul_f32 v[38:39], v[38:39], v[192:193] op_sel:[0,1] op_sel_hi:[1,1]
	v_pk_mul_f32 v[40:41], v[40:41], v[192:193] op_sel:[0,1] op_sel_hi:[1,1]
	v_pk_mul_f32 v[42:43], v[42:43], v[192:193] op_sel:[0,1] op_sel_hi:[1,1]
	v_pk_add_f32 v[48:49], v[48:49], 1.0 op_sel_hi:[1,0]
	v_pk_add_f32 v[52:53], v[52:53], 1.0 op_sel_hi:[1,0]
	v_pk_add_f32 v[54:55], v[54:55], 1.0 op_sel_hi:[1,0]
	v_pk_add_f32 v[56:57], v[56:57], 1.0 op_sel_hi:[1,0]
	v_rcp_f32_e32 v48, v48
	v_rcp_f32_e32 v49, v49
	v_rcp_f32_e32 v52, v52
	v_rcp_f32_e32 v53, v53
	v_rcp_f32_e32 v54, v54
	v_rcp_f32_e32 v55, v55
	v_rcp_f32_e32 v56, v56
	v_rcp_f32_e32 v57, v57
	v_pk_mul_f32 v[36:37], v[36:37], v[48:49]
	v_pk_mul_f32 v[38:39], v[38:39], v[52:53]
	v_pk_mul_f32 v[40:41], v[40:41], v[54:55]
	v_pk_mul_f32 v[42:43], v[42:43], v[56:57]
	v_cvt_pk_bf16_f32 v32, v36, v37
	v_cvt_pk_bf16_f32 v33, v38, v39
	v_cvt_pk_bf16_f32 v34, v40, v41
	v_cvt_pk_bf16_f32 v35, v42, v43
	global_store_dwordx4 v[50:51], v[32:35], off nt
	s_nop 0
	s_waitcnt vmcnt(7)
	v_cvt_f32_u32_e32 v32, v195
	v_cvt_f32_u32_e32 v34, v194
	v_add_u32_e32 v33, 0xa0, v144
	v_fmamk_f32 v32, v34, 0x2f800000, v32
	v_fmamk_f32 v32, v32, 0x3a800000, v158
	v_rsq_f32_e32 v32, v32
	v_mad_i64_i32 v[34:35], s[54:55], v33, s67, v[146:147]
	v_lshl_add_u64 v[34:35], v[34:35], 0, v[148:149]
	v_mul_f32_e32 v194, 0xbfb8aa3b, v32
	v_mul_f32_e32 v195, v32, v32
	v_pk_mul_f32 v[32:33], v[28:29], v[194:195] op_sel_hi:[1,0]
	v_pk_mul_f32 v[36:37], v[30:31], v[194:195] op_sel_hi:[1,0]
	v_pk_mul_f32 v[38:39], v[24:25], v[194:195] op_sel_hi:[1,0]
	v_pk_mul_f32 v[40:41], v[26:27], v[194:195] op_sel_hi:[1,0]
	v_pk_mul_f32 v[20:21], v[20:21], v[28:29]
	v_pk_mul_f32 v[22:23], v[22:23], v[30:31]
	v_pk_mul_f32 v[24:25], v[16:17], v[24:25]
	v_pk_mul_f32 v[26:27], v[18:19], v[26:27]
	v_exp_f32_e32 v32, v32
	v_exp_f32_e32 v33, v33
	v_exp_f32_e32 v36, v36
	v_exp_f32_e32 v37, v37
	v_exp_f32_e32 v38, v38
	v_exp_f32_e32 v39, v39
	v_exp_f32_e32 v40, v40
	v_exp_f32_e32 v41, v41
	v_pk_mul_f32 v[20:21], v[20:21], v[194:195] op_sel:[0,1] op_sel_hi:[1,1]
	v_pk_mul_f32 v[22:23], v[22:23], v[194:195] op_sel:[0,1] op_sel_hi:[1,1]
	v_pk_mul_f32 v[24:25], v[24:25], v[194:195] op_sel:[0,1] op_sel_hi:[1,1]
	v_pk_mul_f32 v[26:27], v[26:27], v[194:195] op_sel:[0,1] op_sel_hi:[1,1]
	v_pk_add_f32 v[32:33], v[32:33], 1.0 op_sel_hi:[1,0]
	v_pk_add_f32 v[36:37], v[36:37], 1.0 op_sel_hi:[1,0]
	v_pk_add_f32 v[38:39], v[38:39], 1.0 op_sel_hi:[1,0]
	v_pk_add_f32 v[40:41], v[40:41], 1.0 op_sel_hi:[1,0]
	v_rcp_f32_e32 v32, v32
	v_rcp_f32_e32 v33, v33
	v_rcp_f32_e32 v36, v36
	v_rcp_f32_e32 v37, v37
	v_rcp_f32_e32 v38, v38
	v_rcp_f32_e32 v39, v39
	v_rcp_f32_e32 v40, v40
	v_rcp_f32_e32 v41, v41
	v_pk_mul_f32 v[20:21], v[20:21], v[32:33]
	v_pk_mul_f32 v[22:23], v[22:23], v[36:37]
	v_pk_mul_f32 v[24:25], v[24:25], v[38:39]
	v_pk_mul_f32 v[26:27], v[26:27], v[40:41]
	v_cvt_pk_bf16_f32 v16, v20, v21
	v_cvt_pk_bf16_f32 v17, v22, v23
	v_cvt_pk_bf16_f32 v18, v24, v25
	v_cvt_pk_bf16_f32 v19, v26, v27
	global_store_dwordx4 v[34:35], v[16:19], off nt
	s_nop 0
	s_waitcnt vmcnt(7)
	v_cvt_f32_u32_e32 v16, v197
	v_cvt_f32_u32_e32 v18, v196
	v_add_u32_e32 v17, 0xb0, v144
	v_fmamk_f32 v16, v18, 0x2f800000, v16
	v_fmamk_f32 v16, v16, 0x3a800000, v158
	v_rsq_f32_e32 v16, v16
	v_mad_i64_i32 v[18:19], s[54:55], v17, s67, v[146:147]
	v_lshl_add_u64 v[18:19], v[18:19], 0, v[148:149]
	v_mul_f32_e32 v196, 0xbfb8aa3b, v16
	v_mul_f32_e32 v197, v16, v16
	v_pk_mul_f32 v[16:17], v[12:13], v[196:197] op_sel_hi:[1,0]
	v_pk_mul_f32 v[20:21], v[14:15], v[196:197] op_sel_hi:[1,0]
	v_pk_mul_f32 v[22:23], v[8:9], v[196:197] op_sel_hi:[1,0]
	v_pk_mul_f32 v[24:25], v[10:11], v[196:197] op_sel_hi:[1,0]
	v_pk_mul_f32 v[4:5], v[4:5], v[12:13]
	v_pk_mul_f32 v[6:7], v[6:7], v[14:15]
	v_pk_mul_f32 v[8:9], v[0:1], v[8:9]
	v_pk_mul_f32 v[10:11], v[2:3], v[10:11]
	v_exp_f32_e32 v16, v16
	v_exp_f32_e32 v17, v17
	v_exp_f32_e32 v20, v20
	v_exp_f32_e32 v21, v21
	v_exp_f32_e32 v22, v22
	v_exp_f32_e32 v23, v23
	v_exp_f32_e32 v24, v24
	v_exp_f32_e32 v25, v25
	v_pk_mul_f32 v[4:5], v[4:5], v[196:197] op_sel:[0,1] op_sel_hi:[1,1]
	v_pk_mul_f32 v[6:7], v[6:7], v[196:197] op_sel:[0,1] op_sel_hi:[1,1]
	v_pk_mul_f32 v[8:9], v[8:9], v[196:197] op_sel:[0,1] op_sel_hi:[1,1]
	v_pk_mul_f32 v[10:11], v[10:11], v[196:197] op_sel:[0,1] op_sel_hi:[1,1]
	v_pk_add_f32 v[16:17], v[16:17], 1.0 op_sel_hi:[1,0]
	v_pk_add_f32 v[20:21], v[20:21], 1.0 op_sel_hi:[1,0]
	v_pk_add_f32 v[22:23], v[22:23], 1.0 op_sel_hi:[1,0]
	v_pk_add_f32 v[24:25], v[24:25], 1.0 op_sel_hi:[1,0]
	v_rcp_f32_e32 v16, v16
	v_rcp_f32_e32 v17, v17
	v_rcp_f32_e32 v20, v20
	v_rcp_f32_e32 v21, v21
	v_rcp_f32_e32 v22, v22
	v_rcp_f32_e32 v23, v23
	v_rcp_f32_e32 v24, v24
	v_rcp_f32_e32 v25, v25
	v_pk_mul_f32 v[4:5], v[4:5], v[16:17]
	v_pk_mul_f32 v[6:7], v[6:7], v[20:21]
	v_pk_mul_f32 v[8:9], v[8:9], v[22:23]
	v_pk_mul_f32 v[10:11], v[10:11], v[24:25]
	v_cvt_pk_bf16_f32 v0, v4, v5
	v_cvt_pk_bf16_f32 v1, v6, v7
	v_cvt_pk_bf16_f32 v2, v8, v9
	v_cvt_pk_bf16_f32 v3, v10, v11
	global_store_dwordx4 v[18:19], v[0:3], off nt
	s_cbranch_vccnz .LBB0_953
	s_andn2_b64 vcc, exec, s[12:13]
	s_cbranch_vccnz .LBB0_952
	s_barrier
	s_branch .LBB0_952

; __device__ __forceinline__ unsigned cvtpk(float lo, float hi) { f32x2v_ v = {lo, hi}; bf16x2v_ b = __builtin_convertvector(v, bf16x2v_); return __builtin_bit_cast(unsigned, b); }
; __device__ __forceinline__ float row_rs(const float* ssp, int row) { const unsigned long long v = ((const unsigned long long*)ssp)[row];
;     return __builtin_amdgcn_rsqf((float)v * (1.0f / 4294967296.0f) * (1.0f / 1024.0f) + RMS_EPS); }
;     __device__ __forceinline__ void operator()(const f32x4 (&acc)[2][2][4][2], const Unit& u, int wr, int wc, int fr, int fq) const {
;         const int row0 = u.pm * BM + wr * 64 + fr, col0 = u.pn * HALF + wc * 32 + 8 * fq;
; #pragma unroll
;         for (int ai = 0; ai < 2; ++ai)
; #pragma unroll
;             for (int m = 0; m < 4; ++m) { const int row = row0 + ai * HALF + m * 16; const float rs = row_rs(ss, row);
;                 float hv[8];
; #pragma unroll
;                 for (int n = 0; n < 2; ++n)
; #pragma unroll
;                     for (int i = 0; i < 4; ++i) { const float g = acc[ai][0][m][n][i] * rs, uu = acc[ai][1][m][n][i] * rs;
;                         hv[n * 4 + i] = g * __builtin_amdgcn_rcpf(1.0f + __expf(-g)) * uu; }
;                 u32x4 w; w.x = cvtpk(hv[0], hv[1]); w.y = cvtpk(hv[2], hv[3]); w.z = cvtpk(hv[4], hv[5]); w.w = cvtpk(hv[6], hv[7]);
;                 *(u32x4*)(H + (size_t)row * ldh + col0) = w; }
.LBB0_1122:
	v_lshl_or_b32 v160, s75, 7, v154
	v_ashrrev_i32_e32 v161, 31, v160
	v_or_b32_e32 v164, 16, v144
	v_ashrrev_i32_e32 v165, 31, v164
	v_lshl_add_u64 v[166:167], v[164:165], 3, s[36:37]
	v_mov_b64_e32 v[146:147], s[20:21]
	v_mad_i64_i32 v[162:163], s[54:55], v144, s74, v[146:147]
	s_andn2_b64 vcc, exec, s[10:11]
	s_mov_b64 s[10:11], -1
	s_waitcnt vmcnt(7)
	v_cvt_f32_u32_e32 v159, v183
	v_cvt_f32_u32_e32 v145, v182
	v_lshlrev_b64 v[148:149], 1, v[160:161]
	v_lshl_add_u64 v[162:163], v[162:163], 0, v[148:149]
	v_fmamk_f32 v145, v145, 0x2f800000, v159
	v_fmamk_f32 v145, v145, 0x3a800000, v158
	v_rsq_f32_e32 v160, v145
	s_nop 0
	v_mul_f32_e32 v182, 0xbfb8aa3b, v160
	v_mul_f32_e32 v183, v160, v160
	v_pk_mul_f32 v[160:161], v[124:125], v[182:183] op_sel_hi:[1,0]
	v_pk_mul_f32 v[168:169], v[126:127], v[182:183] op_sel_hi:[1,0]
	v_pk_mul_f32 v[170:171], v[120:121], v[182:183] op_sel_hi:[1,0]
	v_pk_mul_f32 v[172:173], v[122:123], v[182:183] op_sel_hi:[1,0]
	v_pk_mul_f32 v[116:117], v[116:117], v[124:125]
	v_pk_mul_f32 v[118:119], v[118:119], v[126:127]
	v_pk_mul_f32 v[120:121], v[112:113], v[120:121]
	v_pk_mul_f32 v[122:123], v[114:115], v[122:123]
	v_exp_f32_e32 v160, v160
	v_exp_f32_e32 v161, v161
	v_exp_f32_e32 v168, v168
	v_exp_f32_e32 v169, v169
	v_exp_f32_e32 v170, v170
	v_exp_f32_e32 v171, v171
	v_exp_f32_e32 v172, v172
	v_exp_f32_e32 v173, v173
	v_pk_mul_f32 v[116:117], v[116:117], v[182:183] op_sel:[0,1] op_sel_hi:[1,1]
	v_pk_mul_f32 v[118:119], v[118:119], v[182:183] op_sel:[0,1] op_sel_hi:[1,1]
	v_pk_mul_f32 v[120:121], v[120:121], v[182:183] op_sel:[0,1] op_sel_hi:[1,1]
	v_pk_mul_f32 v[122:123], v[122:123], v[182:183] op_sel:[0,1] op_sel_hi:[1,1]
	v_pk_add_f32 v[160:161], v[160:161], 1.0 op_sel_hi:[1,0]
	v_pk_add_f32 v[168:169], v[168:169], 1.0 op_sel_hi:[1,0]
	v_pk_add_f32 v[170:171], v[170:171], 1.0 op_sel_hi:[1,0]
	v_pk_add_f32 v[172:173], v[172:173], 1.0 op_sel_hi:[1,0]
	v_rcp_f32_e32 v160, v160
	v_rcp_f32_e32 v161, v161
	v_rcp_f32_e32 v168, v168
	v_rcp_f32_e32 v169, v169
	v_rcp_f32_e32 v170, v170
	v_rcp_f32_e32 v171, v171
	v_rcp_f32_e32 v172, v172
	v_rcp_f32_e32 v173, v173
	v_pk_mul_f32 v[116:117], v[116:117], v[160:161]
	v_pk_mul_f32 v[118:119], v[118:119], v[168:169]
	v_pk_mul_f32 v[120:121], v[120:121], v[170:171]
	v_pk_mul_f32 v[122:123], v[122:123], v[172:173]
	v_cvt_pk_bf16_f32 v112, v116, v117
	v_cvt_pk_bf16_f32 v113, v118, v119
	v_cvt_pk_bf16_f32 v114, v120, v121
	v_cvt_pk_bf16_f32 v115, v122, v123
	global_store_dwordx4 v[162:163], v[112:115], off nt
	s_nop 0
	s_nop 0
	v_or_b32_e32 v114, 32, v144
	s_waitcnt vmcnt(7)
	v_cvt_f32_u32_e32 v116, v185
	v_cvt_f32_u32_e32 v115, v184
	v_mad_i64_i32 v[112:113], s[54:55], v164, s74, v[146:147]
	v_fmamk_f32 v115, v115, 0x2f800000, v116
	v_fmamk_f32 v115, v115, 0x3a800000, v158
	v_rsq_f32_e32 v116, v115
	v_ashrrev_i32_e32 v115, 31, v114
	v_lshl_add_u64 v[118:119], v[114:115], 3, s[36:37]
	v_lshl_add_u64 v[112:113], v[112:113], 0, v[148:149]
	v_mul_f32_e32 v184, 0xbfb8aa3b, v116
	v_mul_f32_e32 v185, v116, v116
	v_pk_mul_f32 v[116:117], v[108:109], v[184:185] op_sel_hi:[1,0]
	v_pk_mul_f32 v[120:121], v[110:111], v[184:185] op_sel_hi:[1,0]
	v_pk_mul_f32 v[122:123], v[104:105], v[184:185] op_sel_hi:[1,0]
	v_pk_mul_f32 v[124:125], v[106:107], v[184:185] op_sel_hi:[1,0]
	v_pk_mul_f32 v[100:101], v[100:101], v[108:109]
	v_pk_mul_f32 v[102:103], v[102:103], v[110:111]
	v_pk_mul_f32 v[104:105], v[96:97], v[104:105]
	v_pk_mul_f32 v[106:107], v[98:99], v[106:107]
	v_exp_f32_e32 v116, v116
	v_exp_f32_e32 v117, v117
	v_exp_f32_e32 v120, v120
	v_exp_f32_e32 v121, v121
	v_exp_f32_e32 v122, v122
	v_exp_f32_e32 v123, v123
	v_exp_f32_e32 v124, v124
	v_exp_f32_e32 v125, v125
	v_pk_mul_f32 v[100:101], v[100:101], v[184:185] op_sel:[0,1] op_sel_hi:[1,1]
	v_pk_mul_f32 v[102:103], v[102:103], v[184:185] op_sel:[0,1] op_sel_hi:[1,1]
	v_pk_mul_f32 v[104:105], v[104:105], v[184:185] op_sel:[0,1] op_sel_hi:[1,1]
	v_pk_mul_f32 v[106:107], v[106:107], v[184:185] op_sel:[0,1] op_sel_hi:[1,1]
	v_pk_add_f32 v[116:117], v[116:117], 1.0 op_sel_hi:[1,0]
	v_pk_add_f32 v[120:121], v[120:121], 1.0 op_sel_hi:[1,0]
	v_pk_add_f32 v[122:123], v[122:123], 1.0 op_sel_hi:[1,0]
	v_pk_add_f32 v[124:125], v[124:125], 1.0 op_sel_hi:[1,0]
	v_rcp_f32_e32 v116, v116
	v_rcp_f32_e32 v117, v117
	v_rcp_f32_e32 v120, v120
	v_rcp_f32_e32 v121, v121
	v_rcp_f32_e32 v122, v122
	v_rcp_f32_e32 v123, v123
	v_rcp_f32_e32 v124, v124
	v_rcp_f32_e32 v125, v125
	v_pk_mul_f32 v[100:101], v[100:101], v[116:117]
	v_pk_mul_f32 v[102:103], v[102:103], v[120:121]
	v_pk_mul_f32 v[104:105], v[104:105], v[122:123]
	v_pk_mul_f32 v[106:107], v[106:107], v[124:125]
	v_cvt_pk_bf16_f32 v96, v100, v101
	v_cvt_pk_bf16_f32 v97, v102, v103
	v_cvt_pk_bf16_f32 v98, v104, v105
	v_cvt_pk_bf16_f32 v99, v106, v107
	global_store_dwordx4 v[112:113], v[96:99], off nt
	s_nop 0
	s_nop 0
	v_or_b32_e32 v98, 48, v144
	s_waitcnt vmcnt(7)
; __device__ __forceinline__ unsigned cvtpk(float lo, float hi) { f32x2v_ v = {lo, hi}; bf16x2v_ b = __builtin_convertvector(v, bf16x2v_); return __builtin_bit_cast(unsigned, b); }
; __device__ __forceinline__ float row_rs(const float* ssp, int row) { const unsigned long long v = ((const unsigned long long*)ssp)[row];
;     return __builtin_amdgcn_rsqf((float)v * (1.0f / 4294967296.0f) * (1.0f / 1024.0f) + RMS_EPS); }
;     __device__ __forceinline__ void operator()(const f32x4 (&acc)[2][2][4][2], const Unit& u, int wr, int wc, int fr, int fq) const {
;     ...
;             for (int m = 0; m < 4; ++m) { const int row = row0 + ai * HALF + m * 16; const float rs = row_rs(ss, row);
;                 float hv[8];
; #pragma unroll
;                 for (int n = 0; n < 2; ++n)
; #pragma unroll
;                     for (int i = 0; i < 4; ++i) { const float g = acc[ai][0][m][n][i] * rs, uu = acc[ai][1][m][n][i] * rs;
;                         hv[n * 4 + i] = g * __builtin_amdgcn_rcpf(1.0f + __expf(-g)) * uu; }
;                 u32x4 w; w.x = cvtpk(hv[0], hv[1]); w.y = cvtpk(hv[2], hv[3]); w.z = cvtpk(hv[4], hv[5]); w.w = cvtpk(hv[6], hv[7]);
;                 *(u32x4*)(H + (size_t)row * ldh + col0) = w; }
	v_cvt_f32_u32_e32 v100, v187
	v_cvt_f32_u32_e32 v99, v186
	v_mad_i64_i32 v[96:97], s[54:55], v114, s74, v[146:147]
	v_fmamk_f32 v99, v99, 0x2f800000, v100
	v_fmamk_f32 v99, v99, 0x3a800000, v158
	v_rsq_f32_e32 v100, v99
	v_ashrrev_i32_e32 v99, 31, v98
	v_lshl_add_u64 v[102:103], v[98:99], 3, s[36:37]
	v_lshl_add_u64 v[96:97], v[96:97], 0, v[148:149]
	v_mul_f32_e32 v186, 0xbfb8aa3b, v100
	v_mul_f32_e32 v187, v100, v100
	v_pk_mul_f32 v[100:101], v[92:93], v[186:187] op_sel_hi:[1,0]
	v_pk_mul_f32 v[104:105], v[94:95], v[186:187] op_sel_hi:[1,0]
	v_pk_mul_f32 v[106:107], v[88:89], v[186:187] op_sel_hi:[1,0]
	v_pk_mul_f32 v[108:109], v[90:91], v[186:187] op_sel_hi:[1,0]
	v_pk_mul_f32 v[84:85], v[84:85], v[92:93]
	v_pk_mul_f32 v[86:87], v[86:87], v[94:95]
	v_pk_mul_f32 v[88:89], v[80:81], v[88:89]
	v_pk_mul_f32 v[90:91], v[82:83], v[90:91]
	v_exp_f32_e32 v100, v100
	v_exp_f32_e32 v101, v101
	v_exp_f32_e32 v104, v104
	v_exp_f32_e32 v105, v105
	v_exp_f32_e32 v106, v106
	v_exp_f32_e32 v107, v107
	v_exp_f32_e32 v108, v108
	v_exp_f32_e32 v109, v109
	v_pk_mul_f32 v[84:85], v[84:85], v[186:187] op_sel:[0,1] op_sel_hi:[1,1]
	v_pk_mul_f32 v[86:87], v[86:87], v[186:187] op_sel:[0,1] op_sel_hi:[1,1]
	v_pk_mul_f32 v[88:89], v[88:89], v[186:187] op_sel:[0,1] op_sel_hi:[1,1]
	v_pk_mul_f32 v[90:91], v[90:91], v[186:187] op_sel:[0,1] op_sel_hi:[1,1]
	v_pk_add_f32 v[100:101], v[100:101], 1.0 op_sel_hi:[1,0]
	v_pk_add_f32 v[104:105], v[104:105], 1.0 op_sel_hi:[1,0]
	v_pk_add_f32 v[106:107], v[106:107], 1.0 op_sel_hi:[1,0]
	v_pk_add_f32 v[108:109], v[108:109], 1.0 op_sel_hi:[1,0]
	v_rcp_f32_e32 v100, v100
	v_rcp_f32_e32 v101, v101
	v_rcp_f32_e32 v104, v104
	v_rcp_f32_e32 v105, v105
	v_rcp_f32_e32 v106, v106
	v_rcp_f32_e32 v107, v107
	v_rcp_f32_e32 v108, v108
	v_rcp_f32_e32 v109, v109
	v_pk_mul_f32 v[84:85], v[84:85], v[100:101]
	v_pk_mul_f32 v[86:87], v[86:87], v[104:105]
	v_pk_mul_f32 v[88:89], v[88:89], v[106:107]
	v_pk_mul_f32 v[90:91], v[90:91], v[108:109]
	v_cvt_pk_bf16_f32 v80, v84, v85
	v_cvt_pk_bf16_f32 v81, v86, v87
	v_cvt_pk_bf16_f32 v82, v88, v89
	v_cvt_pk_bf16_f32 v83, v90, v91
	global_store_dwordx4 v[96:97], v[80:83], off nt
	s_nop 0
	s_waitcnt vmcnt(7)
	v_cvt_f32_u32_e32 v80, v189
	v_cvt_f32_u32_e32 v81, v188
	v_mad_i64_i32 v[82:83], s[54:55], v98, s74, v[146:147]
	v_fmamk_f32 v80, v81, 0x2f800000, v80
	v_fmamk_f32 v80, v80, 0x3a800000, v158
	v_rsq_f32_e32 v80, v80
	v_lshl_add_u64 v[82:83], v[82:83], 0, v[148:149]
	v_mul_f32_e32 v188, 0xbfb8aa3b, v80
	v_mul_f32_e32 v189, v80, v80
	v_pk_mul_f32 v[80:81], v[76:77], v[188:189] op_sel_hi:[1,0]
	v_pk_mul_f32 v[84:85], v[78:79], v[188:189] op_sel_hi:[1,0]
	v_pk_mul_f32 v[86:87], v[72:73], v[188:189] op_sel_hi:[1,0]
	v_pk_mul_f32 v[88:89], v[74:75], v[188:189] op_sel_hi:[1,0]
	v_pk_mul_f32 v[68:69], v[68:69], v[76:77]
	v_pk_mul_f32 v[70:71], v[70:71], v[78:79]
	v_pk_mul_f32 v[72:73], v[64:65], v[72:73]
	v_pk_mul_f32 v[74:75], v[66:67], v[74:75]
	v_exp_f32_e32 v80, v80
	v_exp_f32_e32 v81, v81
	v_exp_f32_e32 v84, v84
	v_exp_f32_e32 v85, v85
	v_exp_f32_e32 v86, v86
	v_exp_f32_e32 v87, v87
	v_exp_f32_e32 v88, v88
	v_exp_f32_e32 v89, v89
	v_pk_mul_f32 v[68:69], v[68:69], v[188:189] op_sel:[0,1] op_sel_hi:[1,1]
	v_pk_mul_f32 v[70:71], v[70:71], v[188:189] op_sel:[0,1] op_sel_hi:[1,1]
	v_pk_mul_f32 v[72:73], v[72:73], v[188:189] op_sel:[0,1] op_sel_hi:[1,1]
	v_pk_mul_f32 v[74:75], v[74:75], v[188:189] op_sel:[0,1] op_sel_hi:[1,1]
	v_pk_add_f32 v[80:81], v[80:81], 1.0 op_sel_hi:[1,0]
	v_pk_add_f32 v[84:85], v[84:85], 1.0 op_sel_hi:[1,0]
	v_pk_add_f32 v[86:87], v[86:87], 1.0 op_sel_hi:[1,0]
	v_pk_add_f32 v[88:89], v[88:89], 1.0 op_sel_hi:[1,0]
	v_rcp_f32_e32 v80, v80
	v_rcp_f32_e32 v81, v81
	v_rcp_f32_e32 v84, v84
	v_rcp_f32_e32 v85, v85
	v_rcp_f32_e32 v86, v86
	v_rcp_f32_e32 v87, v87
	v_rcp_f32_e32 v88, v88
	v_rcp_f32_e32 v89, v89
	v_pk_mul_f32 v[68:69], v[68:69], v[80:81]
	v_pk_mul_f32 v[70:71], v[70:71], v[84:85]
	v_pk_mul_f32 v[72:73], v[72:73], v[86:87]
	v_pk_mul_f32 v[74:75], v[74:75], v[88:89]
	v_cvt_pk_bf16_f32 v64, v68, v69
	v_cvt_pk_bf16_f32 v65, v70, v71
	v_cvt_pk_bf16_f32 v66, v72, v73
	v_cvt_pk_bf16_f32 v67, v74, v75
	global_store_dwordx4 v[82:83], v[64:67], off nt
	s_nop 0
	s_waitcnt vmcnt(7)
	v_cvt_f32_u32_e32 v64, v191
	v_cvt_f32_u32_e32 v66, v190
	v_add_u32_e32 v65, 0x80, v144
	v_fmamk_f32 v64, v66, 0x2f800000, v64
	v_fmamk_f32 v64, v64, 0x3a800000, v158
	v_rsq_f32_e32 v64, v64
	v_mad_i64_i32 v[66:67], s[54:55], v65, s74, v[146:147]
	v_lshl_add_u64 v[66:67], v[66:67], 0, v[148:149]
	v_mul_f32_e32 v190, 0xbfb8aa3b, v64
	v_mul_f32_e32 v191, v64, v64
	v_pk_mul_f32 v[64:65], v[60:61], v[190:191] op_sel_hi:[1,0]
	v_pk_mul_f32 v[68:69], v[62:63], v[190:191] op_sel_hi:[1,0]
	v_pk_mul_f32 v[70:71], v[56:57], v[190:191] op_sel_hi:[1,0]
	v_pk_mul_f32 v[72:73], v[58:59], v[190:191] op_sel_hi:[1,0]
	v_pk_mul_f32 v[52:53], v[52:53], v[60:61]
	v_pk_mul_f32 v[54:55], v[54:55], v[62:63]
	v_pk_mul_f32 v[56:57], v[48:49], v[56:57]
	v_pk_mul_f32 v[58:59], v[50:51], v[58:59]
	v_exp_f32_e32 v64, v64
	v_exp_f32_e32 v65, v65
	v_exp_f32_e32 v68, v68
	v_exp_f32_e32 v69, v69
	v_exp_f32_e32 v70, v70
	v_exp_f32_e32 v71, v71
	v_exp_f32_e32 v72, v72
	v_exp_f32_e32 v73, v73
	v_pk_mul_f32 v[52:53], v[52:53], v[190:191] op_sel:[0,1] op_sel_hi:[1,1]
	v_pk_mul_f32 v[54:55], v[54:55], v[190:191] op_sel:[0,1] op_sel_hi:[1,1]
	v_pk_mul_f32 v[56:57], v[56:57], v[190:191] op_sel:[0,1] op_sel_hi:[1,1]
	v_pk_mul_f32 v[58:59], v[58:59], v[190:191] op_sel:[0,1] op_sel_hi:[1,1]
	v_pk_add_f32 v[64:65], v[64:65], 1.0 op_sel_hi:[1,0]
	v_pk_add_f32 v[68:69], v[68:69], 1.0 op_sel_hi:[1,0]
	v_pk_add_f32 v[70:71], v[70:71], 1.0 op_sel_hi:[1,0]
	v_pk_add_f32 v[72:73], v[72:73], 1.0 op_sel_hi:[1,0]
	v_rcp_f32_e32 v64, v64
	v_rcp_f32_e32 v65, v65
	v_rcp_f32_e32 v68, v68
	v_rcp_f32_e32 v69, v69
	v_rcp_f32_e32 v70, v70
	v_rcp_f32_e32 v71, v71
	v_rcp_f32_e32 v72, v72
	v_rcp_f32_e32 v73, v73
	v_pk_mul_f32 v[52:53], v[52:53], v[64:65]
	v_pk_mul_f32 v[54:55], v[54:55], v[68:69]
	v_pk_mul_f32 v[56:57], v[56:57], v[70:71]
	v_pk_mul_f32 v[58:59], v[58:59], v[72:73]
	v_cvt_pk_bf16_f32 v48, v52, v53
	v_cvt_pk_bf16_f32 v49, v54, v55
	v_cvt_pk_bf16_f32 v50, v56, v57
	v_cvt_pk_bf16_f32 v51, v58, v59
	global_store_dwordx4 v[66:67], v[48:51], off nt
	s_nop 0
	s_waitcnt vmcnt(7)
; __device__ __forceinline__ unsigned cvtpk(float lo, float hi) { f32x2v_ v = {lo, hi}; bf16x2v_ b = __builtin_convertvector(v, bf16x2v_); return __builtin_bit_cast(unsigned, b); }
; #define PG8_BAR __builtin_amdgcn_s_barrier()
;     __device__ __forceinline__ void operator()(const f32x4 (&acc)[2][2][4][2], const Unit& u, int wr, int wc, int fr, int fq) const {
;     ...
;             for (int m = 0; m < 4; ++m) { const int row = row0 + ai * HALF + m * 16; const float rs = row_rs(ss, row);
;                 float hv[8];
; #pragma unroll
;                 for (int n = 0; n < 2; ++n)
; #pragma unroll
;                     for (int i = 0; i < 4; ++i) { const float g = acc[ai][0][m][n][i] * rs, uu = acc[ai][1][m][n][i] * rs;
;                         hv[n * 4 + i] = g * __builtin_amdgcn_rcpf(1.0f + __expf(-g)) * uu; }
;                 u32x4 w; w.x = cvtpk(hv[0], hv[1]); w.y = cvtpk(hv[2], hv[3]); w.z = cvtpk(hv[4], hv[5]); w.w = cvtpk(hv[6], hv[7]);
;                 *(u32x4*)(H + (size_t)row * ldh + col0) = w; }
; template <class Epi, class Sched, bool ALIGN_EPI = false, bool SP2 = false>
; __device__ __forceinline__ void gemm_phase(PG8_LAS unsigned char* lds, const Gemm g, const Sched& S, const Epi& E) {
;     ...
;         if (!has_next) break;
; #pragma unroll
;         for (int a = 0; a < 2; ++a)
; #pragma unroll
;             for (int b = 0; b < 2; ++b)
; #pragma unroll
;                 for (int m = 0; m < 4; ++m)
; #pragma unroll
;                     for (int n = 0; n < 2; ++n) acc[a][b][m][n] = (f32x4){0.f, 0.f, 0.f, 0.f};
;         cur = nxt; cA = nA; cB = nB; ++ui;
;         if constexpr (ALIGN_EPI) { if (wr == 1) PG8_BAR; }
	v_cvt_f32_u32_e32 v48, v193
	v_cvt_f32_u32_e32 v50, v192
	v_add_u32_e32 v49, 0x90, v144
	v_fmamk_f32 v48, v50, 0x2f800000, v48
	v_fmamk_f32 v48, v48, 0x3a800000, v158
	v_rsq_f32_e32 v48, v48
	v_mad_i64_i32 v[50:51], s[54:55], v49, s74, v[146:147]
	v_lshl_add_u64 v[50:51], v[50:51], 0, v[148:149]
	v_mul_f32_e32 v192, 0xbfb8aa3b, v48
	v_mul_f32_e32 v193, v48, v48
	v_pk_mul_f32 v[48:49], v[44:45], v[192:193] op_sel_hi:[1,0]
	v_pk_mul_f32 v[52:53], v[46:47], v[192:193] op_sel_hi:[1,0]
	v_pk_mul_f32 v[54:55], v[40:41], v[192:193] op_sel_hi:[1,0]
	v_pk_mul_f32 v[56:57], v[42:43], v[192:193] op_sel_hi:[1,0]
	v_pk_mul_f32 v[36:37], v[36:37], v[44:45]
	v_pk_mul_f32 v[38:39], v[38:39], v[46:47]
	v_pk_mul_f32 v[40:41], v[32:33], v[40:41]
	v_pk_mul_f32 v[42:43], v[34:35], v[42:43]
	v_exp_f32_e32 v48, v48
	v_exp_f32_e32 v49, v49
	v_exp_f32_e32 v52, v52
	v_exp_f32_e32 v53, v53
	v_exp_f32_e32 v54, v54
	v_exp_f32_e32 v55, v55
	v_exp_f32_e32 v56, v56
	v_exp_f32_e32 v57, v57
	v_pk_mul_f32 v[36:37], v[36:37], v[192:193] op_sel:[0,1] op_sel_hi:[1,1]
	v_pk_mul_f32 v[38:39], v[38:39], v[192:193] op_sel:[0,1] op_sel_hi:[1,1]
	v_pk_mul_f32 v[40:41], v[40:41], v[192:193] op_sel:[0,1] op_sel_hi:[1,1]
	v_pk_mul_f32 v[42:43], v[42:43], v[192:193] op_sel:[0,1] op_sel_hi:[1,1]
	v_pk_add_f32 v[48:49], v[48:49], 1.0 op_sel_hi:[1,0]
	v_pk_add_f32 v[52:53], v[52:53], 1.0 op_sel_hi:[1,0]
	v_pk_add_f32 v[54:55], v[54:55], 1.0 op_sel_hi:[1,0]
	v_pk_add_f32 v[56:57], v[56:57], 1.0 op_sel_hi:[1,0]
	v_rcp_f32_e32 v48, v48
	v_rcp_f32_e32 v49, v49
	v_rcp_f32_e32 v52, v52
	v_rcp_f32_e32 v53, v53
	v_rcp_f32_e32 v54, v54
	v_rcp_f32_e32 v55, v55
	v_rcp_f32_e32 v56, v56
	v_rcp_f32_e32 v57, v57
	v_pk_mul_f32 v[36:37], v[36:37], v[48:49]
	v_pk_mul_f32 v[38:39], v[38:39], v[52:53]
	v_pk_mul_f32 v[40:41], v[40:41], v[54:55]
	v_pk_mul_f32 v[42:43], v[42:43], v[56:57]
	v_cvt_pk_bf16_f32 v32, v36, v37
	v_cvt_pk_bf16_f32 v33, v38, v39
	v_cvt_pk_bf16_f32 v34, v40, v41
	v_cvt_pk_bf16_f32 v35, v42, v43
	global_store_dwordx4 v[50:51], v[32:35], off nt
	s_nop 0
	s_waitcnt vmcnt(7)
	v_cvt_f32_u32_e32 v32, v195
	v_cvt_f32_u32_e32 v34, v194
	v_add_u32_e32 v33, 0xa0, v144
	v_fmamk_f32 v32, v34, 0x2f800000, v32
	v_fmamk_f32 v32, v32, 0x3a800000, v158
	v_rsq_f32_e32 v32, v32
	v_mad_i64_i32 v[34:35], s[54:55], v33, s74, v[146:147]
	v_lshl_add_u64 v[34:35], v[34:35], 0, v[148:149]
	v_mul_f32_e32 v194, 0xbfb8aa3b, v32
	v_mul_f32_e32 v195, v32, v32
	v_pk_mul_f32 v[32:33], v[28:29], v[194:195] op_sel_hi:[1,0]
	v_pk_mul_f32 v[36:37], v[30:31], v[194:195] op_sel_hi:[1,0]
	v_pk_mul_f32 v[38:39], v[24:25], v[194:195] op_sel_hi:[1,0]
	v_pk_mul_f32 v[40:41], v[26:27], v[194:195] op_sel_hi:[1,0]
	v_pk_mul_f32 v[20:21], v[20:21], v[28:29]
	v_pk_mul_f32 v[22:23], v[22:23], v[30:31]
	v_pk_mul_f32 v[24:25], v[16:17], v[24:25]
	v_pk_mul_f32 v[26:27], v[18:19], v[26:27]
	v_exp_f32_e32 v32, v32
	v_exp_f32_e32 v33, v33
	v_exp_f32_e32 v36, v36
	v_exp_f32_e32 v37, v37
	v_exp_f32_e32 v38, v38
	v_exp_f32_e32 v39, v39
	v_exp_f32_e32 v40, v40
	v_exp_f32_e32 v41, v41
	v_pk_mul_f32 v[20:21], v[20:21], v[194:195] op_sel:[0,1] op_sel_hi:[1,1]
	v_pk_mul_f32 v[22:23], v[22:23], v[194:195] op_sel:[0,1] op_sel_hi:[1,1]
	v_pk_mul_f32 v[24:25], v[24:25], v[194:195] op_sel:[0,1] op_sel_hi:[1,1]
	v_pk_mul_f32 v[26:27], v[26:27], v[194:195] op_sel:[0,1] op_sel_hi:[1,1]
	v_pk_add_f32 v[32:33], v[32:33], 1.0 op_sel_hi:[1,0]
	v_pk_add_f32 v[36:37], v[36:37], 1.0 op_sel_hi:[1,0]
	v_pk_add_f32 v[38:39], v[38:39], 1.0 op_sel_hi:[1,0]
	v_pk_add_f32 v[40:41], v[40:41], 1.0 op_sel_hi:[1,0]
	v_rcp_f32_e32 v32, v32
	v_rcp_f32_e32 v33, v33
	v_rcp_f32_e32 v36, v36
	v_rcp_f32_e32 v37, v37
	v_rcp_f32_e32 v38, v38
	v_rcp_f32_e32 v39, v39
	v_rcp_f32_e32 v40, v40
	v_rcp_f32_e32 v41, v41
	v_pk_mul_f32 v[20:21], v[20:21], v[32:33]
	v_pk_mul_f32 v[22:23], v[22:23], v[36:37]
	v_pk_mul_f32 v[24:25], v[24:25], v[38:39]
	v_pk_mul_f32 v[26:27], v[26:27], v[40:41]
	v_cvt_pk_bf16_f32 v16, v20, v21
	v_cvt_pk_bf16_f32 v17, v22, v23
	v_cvt_pk_bf16_f32 v18, v24, v25
	v_cvt_pk_bf16_f32 v19, v26, v27
	global_store_dwordx4 v[34:35], v[16:19], off nt
	s_nop 0
	s_waitcnt vmcnt(7)
	v_cvt_f32_u32_e32 v16, v197
	v_cvt_f32_u32_e32 v18, v196
	v_add_u32_e32 v17, 0xb0, v144
	v_fmamk_f32 v16, v18, 0x2f800000, v16
	v_fmamk_f32 v16, v16, 0x3a800000, v158
	v_rsq_f32_e32 v16, v16
	v_mad_i64_i32 v[18:19], s[54:55], v17, s74, v[146:147]
	v_lshl_add_u64 v[18:19], v[18:19], 0, v[148:149]
	v_mul_f32_e32 v196, 0xbfb8aa3b, v16
	v_mul_f32_e32 v197, v16, v16
	v_pk_mul_f32 v[16:17], v[12:13], v[196:197] op_sel_hi:[1,0]
	v_pk_mul_f32 v[20:21], v[14:15], v[196:197] op_sel_hi:[1,0]
	v_pk_mul_f32 v[22:23], v[8:9], v[196:197] op_sel_hi:[1,0]
	v_pk_mul_f32 v[24:25], v[10:11], v[196:197] op_sel_hi:[1,0]
	v_pk_mul_f32 v[4:5], v[4:5], v[12:13]
	v_pk_mul_f32 v[6:7], v[6:7], v[14:15]
	v_pk_mul_f32 v[8:9], v[0:1], v[8:9]
	v_pk_mul_f32 v[10:11], v[2:3], v[10:11]
	v_exp_f32_e32 v16, v16
	v_exp_f32_e32 v17, v17
	v_exp_f32_e32 v20, v20
	v_exp_f32_e32 v21, v21
	v_exp_f32_e32 v22, v22
	v_exp_f32_e32 v23, v23
	v_exp_f32_e32 v24, v24
	v_exp_f32_e32 v25, v25
	v_pk_mul_f32 v[4:5], v[4:5], v[196:197] op_sel:[0,1] op_sel_hi:[1,1]
	v_pk_mul_f32 v[6:7], v[6:7], v[196:197] op_sel:[0,1] op_sel_hi:[1,1]
	v_pk_mul_f32 v[8:9], v[8:9], v[196:197] op_sel:[0,1] op_sel_hi:[1,1]
	v_pk_mul_f32 v[10:11], v[10:11], v[196:197] op_sel:[0,1] op_sel_hi:[1,1]
	v_pk_add_f32 v[16:17], v[16:17], 1.0 op_sel_hi:[1,0]
	v_pk_add_f32 v[20:21], v[20:21], 1.0 op_sel_hi:[1,0]
	v_pk_add_f32 v[22:23], v[22:23], 1.0 op_sel_hi:[1,0]
	v_pk_add_f32 v[24:25], v[24:25], 1.0 op_sel_hi:[1,0]
	v_rcp_f32_e32 v16, v16
	v_rcp_f32_e32 v17, v17
	v_rcp_f32_e32 v20, v20
	v_rcp_f32_e32 v21, v21
	v_rcp_f32_e32 v22, v22
	v_rcp_f32_e32 v23, v23
	v_rcp_f32_e32 v24, v24
	v_rcp_f32_e32 v25, v25
	v_pk_mul_f32 v[4:5], v[4:5], v[16:17]
	v_pk_mul_f32 v[6:7], v[6:7], v[20:21]
	v_pk_mul_f32 v[8:9], v[8:9], v[22:23]
	v_pk_mul_f32 v[10:11], v[10:11], v[24:25]
	v_cvt_pk_bf16_f32 v0, v4, v5
	v_cvt_pk_bf16_f32 v1, v6, v7
	v_cvt_pk_bf16_f32 v2, v8, v9
	v_cvt_pk_bf16_f32 v3, v10, v11
	global_store_dwordx4 v[18:19], v[0:3], off nt
	s_cbranch_vccnz .LBB0_1115
	s_andn2_b64 vcc, exec, s[0:1]
	s_cbranch_vccnz .LBB0_1114
	s_barrier
	s_branch .LBB0_1114

; __device__ __forceinline__ unsigned cvtpk(float lo, float hi) { f32x2v_ v = {lo, hi}; bf16x2v_ b = __builtin_convertvector(v, bf16x2v_); return __builtin_bit_cast(unsigned, b); }
; __device__ __forceinline__ float row_rs(const float* ssp, int row) { const unsigned long long v = ((const unsigned long long*)ssp)[row];
;     return __builtin_amdgcn_rsqf((float)v * (1.0f / 4294967296.0f) * (1.0f / 1024.0f) + RMS_EPS); }
;     __device__ __forceinline__ void operator()(const f32x4 (&acc)[2][2][4][2], const Unit& u, int wr, int wc, int fr, int fq) const {
;         const int row0 = u.pm * BM + wr * 64 + fr, col0 = u.pn * HALF + wc * 32 + 8 * fq;
; #pragma unroll
;         for (int ai = 0; ai < 2; ++ai)
; #pragma unroll
;             for (int m = 0; m < 4; ++m) { const int row = row0 + ai * HALF + m * 16; const float rs = row_rs(ss, row);
;                 float hv[8];
; #pragma unroll
;                 for (int n = 0; n < 2; ++n)
; #pragma unroll
;                     for (int i = 0; i < 4; ++i) { const float g = acc[ai][0][m][n][i] * rs, uu = acc[ai][1][m][n][i] * rs;
;                         hv[n * 4 + i] = g * __builtin_amdgcn_rcpf(1.0f + __expf(-g)) * uu; }
;                 u32x4 w; w.x = cvtpk(hv[0], hv[1]); w.y = cvtpk(hv[2], hv[3]); w.z = cvtpk(hv[4], hv[5]); w.w = cvtpk(hv[6], hv[7]);
;                 *(u32x4*)(H + (size_t)row * ldh + col0) = w; }
.LBB0_1903:
	v_lshl_or_b32 v160, s52, 7, v154
	v_ashrrev_i32_e32 v161, 31, v160
	v_or_b32_e32 v164, 16, v144
	v_ashrrev_i32_e32 v165, 31, v164
	v_lshl_add_u64 v[166:167], v[164:165], 3, s[0:1]
	v_mov_b64_e32 v[146:147], s[20:21]
	v_mad_i64_i32 v[162:163], s[38:39], v144, s51, v[146:147]
	s_andn2_b64 vcc, exec, s[4:5]
	s_mov_b64 s[4:5], -1
	s_waitcnt vmcnt(7)
	v_cvt_f32_u32_e32 v159, v183
	v_cvt_f32_u32_e32 v145, v182
	v_lshlrev_b64 v[148:149], 1, v[160:161]
	v_lshl_add_u64 v[162:163], v[162:163], 0, v[148:149]
	v_fmamk_f32 v145, v145, 0x2f800000, v159
	v_fmamk_f32 v145, v145, 0x3a800000, v158
	v_rsq_f32_e32 v160, v145
	s_nop 0
	v_mul_f32_e32 v182, 0xbfb8aa3b, v160
	v_mul_f32_e32 v183, v160, v160
	v_pk_mul_f32 v[160:161], v[124:125], v[182:183] op_sel_hi:[1,0]
	v_pk_mul_f32 v[168:169], v[126:127], v[182:183] op_sel_hi:[1,0]
	v_pk_mul_f32 v[170:171], v[120:121], v[182:183] op_sel_hi:[1,0]
	v_pk_mul_f32 v[172:173], v[122:123], v[182:183] op_sel_hi:[1,0]
	v_pk_mul_f32 v[116:117], v[116:117], v[124:125]
	v_pk_mul_f32 v[118:119], v[118:119], v[126:127]
	v_pk_mul_f32 v[120:121], v[112:113], v[120:121]
	v_pk_mul_f32 v[122:123], v[114:115], v[122:123]
	v_exp_f32_e32 v160, v160
	v_exp_f32_e32 v161, v161
	v_exp_f32_e32 v168, v168
	v_exp_f32_e32 v169, v169
	v_exp_f32_e32 v170, v170
	v_exp_f32_e32 v171, v171
	v_exp_f32_e32 v172, v172
	v_exp_f32_e32 v173, v173
	v_pk_mul_f32 v[116:117], v[116:117], v[182:183] op_sel:[0,1] op_sel_hi:[1,1]
	v_pk_mul_f32 v[118:119], v[118:119], v[182:183] op_sel:[0,1] op_sel_hi:[1,1]
	v_pk_mul_f32 v[120:121], v[120:121], v[182:183] op_sel:[0,1] op_sel_hi:[1,1]
	v_pk_mul_f32 v[122:123], v[122:123], v[182:183] op_sel:[0,1] op_sel_hi:[1,1]
	v_pk_add_f32 v[160:161], v[160:161], 1.0 op_sel_hi:[1,0]
	v_pk_add_f32 v[168:169], v[168:169], 1.0 op_sel_hi:[1,0]
	v_pk_add_f32 v[170:171], v[170:171], 1.0 op_sel_hi:[1,0]
	v_pk_add_f32 v[172:173], v[172:173], 1.0 op_sel_hi:[1,0]
	v_rcp_f32_e32 v160, v160
	v_rcp_f32_e32 v161, v161
	v_rcp_f32_e32 v168, v168
	v_rcp_f32_e32 v169, v169
	v_rcp_f32_e32 v170, v170
	v_rcp_f32_e32 v171, v171
	v_rcp_f32_e32 v172, v172
	v_rcp_f32_e32 v173, v173
	v_pk_mul_f32 v[116:117], v[116:117], v[160:161]
	v_pk_mul_f32 v[118:119], v[118:119], v[168:169]
	v_pk_mul_f32 v[120:121], v[120:121], v[170:171]
	v_pk_mul_f32 v[122:123], v[122:123], v[172:173]
	v_cvt_pk_bf16_f32 v112, v116, v117
	v_cvt_pk_bf16_f32 v113, v118, v119
	v_cvt_pk_bf16_f32 v114, v120, v121
	v_cvt_pk_bf16_f32 v115, v122, v123
	global_store_dwordx4 v[162:163], v[112:115], off nt
	s_nop 0
	s_nop 0
	v_or_b32_e32 v114, 32, v144
	s_waitcnt vmcnt(7)
	v_cvt_f32_u32_e32 v116, v185
	v_cvt_f32_u32_e32 v115, v184
	v_mad_i64_i32 v[112:113], s[38:39], v164, s51, v[146:147]
	v_fmamk_f32 v115, v115, 0x2f800000, v116
	v_fmamk_f32 v115, v115, 0x3a800000, v158
	v_rsq_f32_e32 v116, v115
	v_ashrrev_i32_e32 v115, 31, v114
	v_lshl_add_u64 v[118:119], v[114:115], 3, s[0:1]
	v_lshl_add_u64 v[112:113], v[112:113], 0, v[148:149]
	v_mul_f32_e32 v184, 0xbfb8aa3b, v116
	v_mul_f32_e32 v185, v116, v116
	v_pk_mul_f32 v[116:117], v[108:109], v[184:185] op_sel_hi:[1,0]
	v_pk_mul_f32 v[120:121], v[110:111], v[184:185] op_sel_hi:[1,0]
	v_pk_mul_f32 v[122:123], v[104:105], v[184:185] op_sel_hi:[1,0]
	v_pk_mul_f32 v[124:125], v[106:107], v[184:185] op_sel_hi:[1,0]
	v_pk_mul_f32 v[100:101], v[100:101], v[108:109]
	v_pk_mul_f32 v[102:103], v[102:103], v[110:111]
	v_pk_mul_f32 v[104:105], v[96:97], v[104:105]
	v_pk_mul_f32 v[106:107], v[98:99], v[106:107]
	v_exp_f32_e32 v116, v116
	v_exp_f32_e32 v117, v117
	v_exp_f32_e32 v120, v120
	v_exp_f32_e32 v121, v121
	v_exp_f32_e32 v122, v122
	v_exp_f32_e32 v123, v123
	v_exp_f32_e32 v124, v124
	v_exp_f32_e32 v125, v125
	v_pk_mul_f32 v[100:101], v[100:101], v[184:185] op_sel:[0,1] op_sel_hi:[1,1]
	v_pk_mul_f32 v[102:103], v[102:103], v[184:185] op_sel:[0,1] op_sel_hi:[1,1]
	v_pk_mul_f32 v[104:105], v[104:105], v[184:185] op_sel:[0,1] op_sel_hi:[1,1]
	v_pk_mul_f32 v[106:107], v[106:107], v[184:185] op_sel:[0,1] op_sel_hi:[1,1]
	v_pk_add_f32 v[116:117], v[116:117], 1.0 op_sel_hi:[1,0]
	v_pk_add_f32 v[120:121], v[120:121], 1.0 op_sel_hi:[1,0]
	v_pk_add_f32 v[122:123], v[122:123], 1.0 op_sel_hi:[1,0]
	v_pk_add_f32 v[124:125], v[124:125], 1.0 op_sel_hi:[1,0]
	v_rcp_f32_e32 v116, v116
	v_rcp_f32_e32 v117, v117
	v_rcp_f32_e32 v120, v120
	v_rcp_f32_e32 v121, v121
	v_rcp_f32_e32 v122, v122
	v_rcp_f32_e32 v123, v123
	v_rcp_f32_e32 v124, v124
	v_rcp_f32_e32 v125, v125
	v_pk_mul_f32 v[100:101], v[100:101], v[116:117]
	v_pk_mul_f32 v[102:103], v[102:103], v[120:121]
	v_pk_mul_f32 v[104:105], v[104:105], v[122:123]
	v_pk_mul_f32 v[106:107], v[106:107], v[124:125]
	v_cvt_pk_bf16_f32 v96, v100, v101
	v_cvt_pk_bf16_f32 v97, v102, v103
	v_cvt_pk_bf16_f32 v98, v104, v105
	v_cvt_pk_bf16_f32 v99, v106, v107
	global_store_dwordx4 v[112:113], v[96:99], off nt
	s_nop 0
	s_nop 0
	v_or_b32_e32 v98, 48, v144
	s_waitcnt vmcnt(7)
; __device__ __forceinline__ unsigned cvtpk(float lo, float hi) { f32x2v_ v = {lo, hi}; bf16x2v_ b = __builtin_convertvector(v, bf16x2v_); return __builtin_bit_cast(unsigned, b); }
; __device__ __forceinline__ float row_rs(const float* ssp, int row) { const unsigned long long v = ((const unsigned long long*)ssp)[row];
;     return __builtin_amdgcn_rsqf((float)v * (1.0f / 4294967296.0f) * (1.0f / 1024.0f) + RMS_EPS); }
;     __device__ __forceinline__ void operator()(const f32x4 (&acc)[2][2][4][2], const Unit& u, int wr, int wc, int fr, int fq) const {
;     ...
;             for (int m = 0; m < 4; ++m) { const int row = row0 + ai * HALF + m * 16; const float rs = row_rs(ss, row);
;                 float hv[8];
; #pragma unroll
;                 for (int n = 0; n < 2; ++n)
; #pragma unroll
;                     for (int i = 0; i < 4; ++i) { const float g = acc[ai][0][m][n][i] * rs, uu = acc[ai][1][m][n][i] * rs;
;                         hv[n * 4 + i] = g * __builtin_amdgcn_rcpf(1.0f + __expf(-g)) * uu; }
;                 u32x4 w; w.x = cvtpk(hv[0], hv[1]); w.y = cvtpk(hv[2], hv[3]); w.z = cvtpk(hv[4], hv[5]); w.w = cvtpk(hv[6], hv[7]);
;                 *(u32x4*)(H + (size_t)row * ldh + col0) = w; }
	v_cvt_f32_u32_e32 v100, v187
	v_cvt_f32_u32_e32 v99, v186
	v_mad_i64_i32 v[96:97], s[38:39], v114, s51, v[146:147]
	v_fmamk_f32 v99, v99, 0x2f800000, v100
	v_fmamk_f32 v99, v99, 0x3a800000, v158
	v_rsq_f32_e32 v100, v99
	v_ashrrev_i32_e32 v99, 31, v98
	v_lshl_add_u64 v[102:103], v[98:99], 3, s[0:1]
	v_lshl_add_u64 v[96:97], v[96:97], 0, v[148:149]
	v_mul_f32_e32 v186, 0xbfb8aa3b, v100
	v_mul_f32_e32 v187, v100, v100
	v_pk_mul_f32 v[100:101], v[92:93], v[186:187] op_sel_hi:[1,0]
	v_pk_mul_f32 v[104:105], v[94:95], v[186:187] op_sel_hi:[1,0]
	v_pk_mul_f32 v[106:107], v[88:89], v[186:187] op_sel_hi:[1,0]
	v_pk_mul_f32 v[108:109], v[90:91], v[186:187] op_sel_hi:[1,0]
	v_pk_mul_f32 v[84:85], v[84:85], v[92:93]
	v_pk_mul_f32 v[86:87], v[86:87], v[94:95]
	v_pk_mul_f32 v[88:89], v[80:81], v[88:89]
	v_pk_mul_f32 v[90:91], v[82:83], v[90:91]
	v_exp_f32_e32 v100, v100
	v_exp_f32_e32 v101, v101
	v_exp_f32_e32 v104, v104
	v_exp_f32_e32 v105, v105
	v_exp_f32_e32 v106, v106
	v_exp_f32_e32 v107, v107
	v_exp_f32_e32 v108, v108
	v_exp_f32_e32 v109, v109
	v_pk_mul_f32 v[84:85], v[84:85], v[186:187] op_sel:[0,1] op_sel_hi:[1,1]
	v_pk_mul_f32 v[86:87], v[86:87], v[186:187] op_sel:[0,1] op_sel_hi:[1,1]
	v_pk_mul_f32 v[88:89], v[88:89], v[186:187] op_sel:[0,1] op_sel_hi:[1,1]
	v_pk_mul_f32 v[90:91], v[90:91], v[186:187] op_sel:[0,1] op_sel_hi:[1,1]
	v_pk_add_f32 v[100:101], v[100:101], 1.0 op_sel_hi:[1,0]
	v_pk_add_f32 v[104:105], v[104:105], 1.0 op_sel_hi:[1,0]
	v_pk_add_f32 v[106:107], v[106:107], 1.0 op_sel_hi:[1,0]
	v_pk_add_f32 v[108:109], v[108:109], 1.0 op_sel_hi:[1,0]
	v_rcp_f32_e32 v100, v100
	v_rcp_f32_e32 v101, v101
	v_rcp_f32_e32 v104, v104
	v_rcp_f32_e32 v105, v105
	v_rcp_f32_e32 v106, v106
	v_rcp_f32_e32 v107, v107
	v_rcp_f32_e32 v108, v108
	v_rcp_f32_e32 v109, v109
	v_pk_mul_f32 v[84:85], v[84:85], v[100:101]
	v_pk_mul_f32 v[86:87], v[86:87], v[104:105]
	v_pk_mul_f32 v[88:89], v[88:89], v[106:107]
	v_pk_mul_f32 v[90:91], v[90:91], v[108:109]
	v_cvt_pk_bf16_f32 v80, v84, v85
	v_cvt_pk_bf16_f32 v81, v86, v87
	v_cvt_pk_bf16_f32 v82, v88, v89
	v_cvt_pk_bf16_f32 v83, v90, v91
	global_store_dwordx4 v[96:97], v[80:83], off nt
	s_nop 0
	s_waitcnt vmcnt(7)
	v_cvt_f32_u32_e32 v80, v189
	v_cvt_f32_u32_e32 v81, v188
	v_mad_i64_i32 v[82:83], s[38:39], v98, s51, v[146:147]
	v_fmamk_f32 v80, v81, 0x2f800000, v80
	v_fmamk_f32 v80, v80, 0x3a800000, v158
	v_rsq_f32_e32 v80, v80
	v_lshl_add_u64 v[82:83], v[82:83], 0, v[148:149]
	v_mul_f32_e32 v188, 0xbfb8aa3b, v80
	v_mul_f32_e32 v189, v80, v80
	v_pk_mul_f32 v[80:81], v[76:77], v[188:189] op_sel_hi:[1,0]
	v_pk_mul_f32 v[84:85], v[78:79], v[188:189] op_sel_hi:[1,0]
	v_pk_mul_f32 v[86:87], v[72:73], v[188:189] op_sel_hi:[1,0]
	v_pk_mul_f32 v[88:89], v[74:75], v[188:189] op_sel_hi:[1,0]
	v_pk_mul_f32 v[68:69], v[68:69], v[76:77]
	v_pk_mul_f32 v[70:71], v[70:71], v[78:79]
	v_pk_mul_f32 v[72:73], v[64:65], v[72:73]
	v_pk_mul_f32 v[74:75], v[66:67], v[74:75]
	v_exp_f32_e32 v80, v80
	v_exp_f32_e32 v81, v81
	v_exp_f32_e32 v84, v84
	v_exp_f32_e32 v85, v85
	v_exp_f32_e32 v86, v86
	v_exp_f32_e32 v87, v87
	v_exp_f32_e32 v88, v88
	v_exp_f32_e32 v89, v89
	v_pk_mul_f32 v[68:69], v[68:69], v[188:189] op_sel:[0,1] op_sel_hi:[1,1]
	v_pk_mul_f32 v[70:71], v[70:71], v[188:189] op_sel:[0,1] op_sel_hi:[1,1]
	v_pk_mul_f32 v[72:73], v[72:73], v[188:189] op_sel:[0,1] op_sel_hi:[1,1]
	v_pk_mul_f32 v[74:75], v[74:75], v[188:189] op_sel:[0,1] op_sel_hi:[1,1]
	v_pk_add_f32 v[80:81], v[80:81], 1.0 op_sel_hi:[1,0]
	v_pk_add_f32 v[84:85], v[84:85], 1.0 op_sel_hi:[1,0]
	v_pk_add_f32 v[86:87], v[86:87], 1.0 op_sel_hi:[1,0]
	v_pk_add_f32 v[88:89], v[88:89], 1.0 op_sel_hi:[1,0]
	v_rcp_f32_e32 v80, v80
	v_rcp_f32_e32 v81, v81
	v_rcp_f32_e32 v84, v84
	v_rcp_f32_e32 v85, v85
	v_rcp_f32_e32 v86, v86
	v_rcp_f32_e32 v87, v87
	v_rcp_f32_e32 v88, v88
	v_rcp_f32_e32 v89, v89
	v_pk_mul_f32 v[68:69], v[68:69], v[80:81]
	v_pk_mul_f32 v[70:71], v[70:71], v[84:85]
	v_pk_mul_f32 v[72:73], v[72:73], v[86:87]
	v_pk_mul_f32 v[74:75], v[74:75], v[88:89]
	v_cvt_pk_bf16_f32 v64, v68, v69
	v_cvt_pk_bf16_f32 v65, v70, v71
	v_cvt_pk_bf16_f32 v66, v72, v73
	v_cvt_pk_bf16_f32 v67, v74, v75
	global_store_dwordx4 v[82:83], v[64:67], off nt
	s_nop 0
	s_waitcnt vmcnt(7)
	v_cvt_f32_u32_e32 v64, v191
	v_cvt_f32_u32_e32 v66, v190
	v_add_u32_e32 v65, 0x80, v144
	v_fmamk_f32 v64, v66, 0x2f800000, v64
	v_fmamk_f32 v64, v64, 0x3a800000, v158
	v_rsq_f32_e32 v64, v64
	v_mad_i64_i32 v[66:67], s[38:39], v65, s51, v[146:147]
	v_lshl_add_u64 v[66:67], v[66:67], 0, v[148:149]
	v_mul_f32_e32 v190, 0xbfb8aa3b, v64
	v_mul_f32_e32 v191, v64, v64
	v_pk_mul_f32 v[64:65], v[60:61], v[190:191] op_sel_hi:[1,0]
	v_pk_mul_f32 v[68:69], v[62:63], v[190:191] op_sel_hi:[1,0]
	v_pk_mul_f32 v[70:71], v[56:57], v[190:191] op_sel_hi:[1,0]
	v_pk_mul_f32 v[72:73], v[58:59], v[190:191] op_sel_hi:[1,0]
	v_pk_mul_f32 v[52:53], v[52:53], v[60:61]
	v_pk_mul_f32 v[54:55], v[54:55], v[62:63]
	v_pk_mul_f32 v[56:57], v[48:49], v[56:57]
	v_pk_mul_f32 v[58:59], v[50:51], v[58:59]
	v_exp_f32_e32 v64, v64
	v_exp_f32_e32 v65, v65
	v_exp_f32_e32 v68, v68
	v_exp_f32_e32 v69, v69
	v_exp_f32_e32 v70, v70
	v_exp_f32_e32 v71, v71
	v_exp_f32_e32 v72, v72
	v_exp_f32_e32 v73, v73
	v_pk_mul_f32 v[52:53], v[52:53], v[190:191] op_sel:[0,1] op_sel_hi:[1,1]
	v_pk_mul_f32 v[54:55], v[54:55], v[190:191] op_sel:[0,1] op_sel_hi:[1,1]
	v_pk_mul_f32 v[56:57], v[56:57], v[190:191] op_sel:[0,1] op_sel_hi:[1,1]
	v_pk_mul_f32 v[58:59], v[58:59], v[190:191] op_sel:[0,1] op_sel_hi:[1,1]
	v_pk_add_f32 v[64:65], v[64:65], 1.0 op_sel_hi:[1,0]
	v_pk_add_f32 v[68:69], v[68:69], 1.0 op_sel_hi:[1,0]
	v_pk_add_f32 v[70:71], v[70:71], 1.0 op_sel_hi:[1,0]
	v_pk_add_f32 v[72:73], v[72:73], 1.0 op_sel_hi:[1,0]
	v_rcp_f32_e32 v64, v64
	v_rcp_f32_e32 v65, v65
	v_rcp_f32_e32 v68, v68
	v_rcp_f32_e32 v69, v69
	v_rcp_f32_e32 v70, v70
	v_rcp_f32_e32 v71, v71
	v_rcp_f32_e32 v72, v72
	v_rcp_f32_e32 v73, v73
	v_pk_mul_f32 v[52:53], v[52:53], v[64:65]
	v_pk_mul_f32 v[54:55], v[54:55], v[68:69]
	v_pk_mul_f32 v[56:57], v[56:57], v[70:71]
	v_pk_mul_f32 v[58:59], v[58:59], v[72:73]
	v_cvt_pk_bf16_f32 v48, v52, v53
	v_cvt_pk_bf16_f32 v49, v54, v55
	v_cvt_pk_bf16_f32 v50, v56, v57
	v_cvt_pk_bf16_f32 v51, v58, v59
	global_store_dwordx4 v[66:67], v[48:51], off nt
	s_nop 0
	s_waitcnt vmcnt(7)
; __device__ __forceinline__ unsigned cvtpk(float lo, float hi) { f32x2v_ v = {lo, hi}; bf16x2v_ b = __builtin_convertvector(v, bf16x2v_); return __builtin_bit_cast(unsigned, b); }
; #define PG8_BAR __builtin_amdgcn_s_barrier()
;     __device__ __forceinline__ void operator()(const f32x4 (&acc)[2][2][4][2], const Unit& u, int wr, int wc, int fr, int fq) const {
;     ...
;             for (int m = 0; m < 4; ++m) { const int row = row0 + ai * HALF + m * 16; const float rs = row_rs(ss, row);
;                 float hv[8];
; #pragma unroll
;                 for (int n = 0; n < 2; ++n)
; #pragma unroll
;                     for (int i = 0; i < 4; ++i) { const float g = acc[ai][0][m][n][i] * rs, uu = acc[ai][1][m][n][i] * rs;
;                         hv[n * 4 + i] = g * __builtin_amdgcn_rcpf(1.0f + __expf(-g)) * uu; }
;                 u32x4 w; w.x = cvtpk(hv[0], hv[1]); w.y = cvtpk(hv[2], hv[3]); w.z = cvtpk(hv[4], hv[5]); w.w = cvtpk(hv[6], hv[7]);
;                 *(u32x4*)(H + (size_t)row * ldh + col0) = w; }
; template <class Epi, class Sched, bool ALIGN_EPI = false, bool SP2 = false>
; __device__ __forceinline__ void gemm_phase(PG8_LAS unsigned char* lds, const Gemm g, const Sched& S, const Epi& E) {
;     ...
;         if (!has_next) break;
; #pragma unroll
;         for (int a = 0; a < 2; ++a)
; #pragma unroll
;             for (int b = 0; b < 2; ++b)
; #pragma unroll
;                 for (int m = 0; m < 4; ++m)
; #pragma unroll
;                     for (int n = 0; n < 2; ++n) acc[a][b][m][n] = (f32x4){0.f, 0.f, 0.f, 0.f};
;         cur = nxt; cA = nA; cB = nB; ++ui;
;         if constexpr (ALIGN_EPI) { if (wr == 1) PG8_BAR; }
	v_cvt_f32_u32_e32 v48, v193
	v_cvt_f32_u32_e32 v50, v192
	v_add_u32_e32 v49, 0x90, v144
	v_fmamk_f32 v48, v50, 0x2f800000, v48
	v_fmamk_f32 v48, v48, 0x3a800000, v158
	v_rsq_f32_e32 v48, v48
	v_mad_i64_i32 v[50:51], s[38:39], v49, s51, v[146:147]
	v_lshl_add_u64 v[50:51], v[50:51], 0, v[148:149]
	v_mul_f32_e32 v192, 0xbfb8aa3b, v48
	v_mul_f32_e32 v193, v48, v48
	v_pk_mul_f32 v[48:49], v[44:45], v[192:193] op_sel_hi:[1,0]
	v_pk_mul_f32 v[52:53], v[46:47], v[192:193] op_sel_hi:[1,0]
	v_pk_mul_f32 v[54:55], v[40:41], v[192:193] op_sel_hi:[1,0]
	v_pk_mul_f32 v[56:57], v[42:43], v[192:193] op_sel_hi:[1,0]
	v_pk_mul_f32 v[36:37], v[36:37], v[44:45]
	v_pk_mul_f32 v[38:39], v[38:39], v[46:47]
	v_pk_mul_f32 v[40:41], v[32:33], v[40:41]
	v_pk_mul_f32 v[42:43], v[34:35], v[42:43]
	v_exp_f32_e32 v48, v48
	v_exp_f32_e32 v49, v49
	v_exp_f32_e32 v52, v52
	v_exp_f32_e32 v53, v53
	v_exp_f32_e32 v54, v54
	v_exp_f32_e32 v55, v55
	v_exp_f32_e32 v56, v56
	v_exp_f32_e32 v57, v57
	v_pk_mul_f32 v[36:37], v[36:37], v[192:193] op_sel:[0,1] op_sel_hi:[1,1]
	v_pk_mul_f32 v[38:39], v[38:39], v[192:193] op_sel:[0,1] op_sel_hi:[1,1]
	v_pk_mul_f32 v[40:41], v[40:41], v[192:193] op_sel:[0,1] op_sel_hi:[1,1]
	v_pk_mul_f32 v[42:43], v[42:43], v[192:193] op_sel:[0,1] op_sel_hi:[1,1]
	v_pk_add_f32 v[48:49], v[48:49], 1.0 op_sel_hi:[1,0]
	v_pk_add_f32 v[52:53], v[52:53], 1.0 op_sel_hi:[1,0]
	v_pk_add_f32 v[54:55], v[54:55], 1.0 op_sel_hi:[1,0]
	v_pk_add_f32 v[56:57], v[56:57], 1.0 op_sel_hi:[1,0]
	v_rcp_f32_e32 v48, v48
	v_rcp_f32_e32 v49, v49
	v_rcp_f32_e32 v52, v52
	v_rcp_f32_e32 v53, v53
	v_rcp_f32_e32 v54, v54
	v_rcp_f32_e32 v55, v55
	v_rcp_f32_e32 v56, v56
	v_rcp_f32_e32 v57, v57
	v_pk_mul_f32 v[36:37], v[36:37], v[48:49]
	v_pk_mul_f32 v[38:39], v[38:39], v[52:53]
	v_pk_mul_f32 v[40:41], v[40:41], v[54:55]
	v_pk_mul_f32 v[42:43], v[42:43], v[56:57]
	v_cvt_pk_bf16_f32 v32, v36, v37
	v_cvt_pk_bf16_f32 v33, v38, v39
	v_cvt_pk_bf16_f32 v34, v40, v41
	v_cvt_pk_bf16_f32 v35, v42, v43
	global_store_dwordx4 v[50:51], v[32:35], off nt
	s_nop 0
	s_waitcnt vmcnt(7)
	v_cvt_f32_u32_e32 v32, v195
	v_cvt_f32_u32_e32 v34, v194
	v_add_u32_e32 v33, 0xa0, v144
	v_fmamk_f32 v32, v34, 0x2f800000, v32
	v_fmamk_f32 v32, v32, 0x3a800000, v158
	v_rsq_f32_e32 v32, v32
	v_mad_i64_i32 v[34:35], s[38:39], v33, s51, v[146:147]
	v_lshl_add_u64 v[34:35], v[34:35], 0, v[148:149]
	v_mul_f32_e32 v194, 0xbfb8aa3b, v32
	v_mul_f32_e32 v195, v32, v32
	v_pk_mul_f32 v[32:33], v[28:29], v[194:195] op_sel_hi:[1,0]
	v_pk_mul_f32 v[36:37], v[30:31], v[194:195] op_sel_hi:[1,0]
	v_pk_mul_f32 v[38:39], v[24:25], v[194:195] op_sel_hi:[1,0]
	v_pk_mul_f32 v[40:41], v[26:27], v[194:195] op_sel_hi:[1,0]
	v_pk_mul_f32 v[20:21], v[20:21], v[28:29]
	v_pk_mul_f32 v[22:23], v[22:23], v[30:31]
	v_pk_mul_f32 v[24:25], v[16:17], v[24:25]
	v_pk_mul_f32 v[26:27], v[18:19], v[26:27]
	v_exp_f32_e32 v32, v32
	v_exp_f32_e32 v33, v33
	v_exp_f32_e32 v36, v36
	v_exp_f32_e32 v37, v37
	v_exp_f32_e32 v38, v38
	v_exp_f32_e32 v39, v39
	v_exp_f32_e32 v40, v40
	v_exp_f32_e32 v41, v41
	v_pk_mul_f32 v[20:21], v[20:21], v[194:195] op_sel:[0,1] op_sel_hi:[1,1]
	v_pk_mul_f32 v[22:23], v[22:23], v[194:195] op_sel:[0,1] op_sel_hi:[1,1]
	v_pk_mul_f32 v[24:25], v[24:25], v[194:195] op_sel:[0,1] op_sel_hi:[1,1]
	v_pk_mul_f32 v[26:27], v[26:27], v[194:195] op_sel:[0,1] op_sel_hi:[1,1]
	v_pk_add_f32 v[32:33], v[32:33], 1.0 op_sel_hi:[1,0]
	v_pk_add_f32 v[36:37], v[36:37], 1.0 op_sel_hi:[1,0]
	v_pk_add_f32 v[38:39], v[38:39], 1.0 op_sel_hi:[1,0]
	v_pk_add_f32 v[40:41], v[40:41], 1.0 op_sel_hi:[1,0]
	v_rcp_f32_e32 v32, v32
	v_rcp_f32_e32 v33, v33
	v_rcp_f32_e32 v36, v36
	v_rcp_f32_e32 v37, v37
	v_rcp_f32_e32 v38, v38
	v_rcp_f32_e32 v39, v39
	v_rcp_f32_e32 v40, v40
	v_rcp_f32_e32 v41, v41
	v_pk_mul_f32 v[20:21], v[20:21], v[32:33]
	v_pk_mul_f32 v[22:23], v[22:23], v[36:37]
	v_pk_mul_f32 v[24:25], v[24:25], v[38:39]
	v_pk_mul_f32 v[26:27], v[26:27], v[40:41]
	v_cvt_pk_bf16_f32 v16, v20, v21
	v_cvt_pk_bf16_f32 v17, v22, v23
	v_cvt_pk_bf16_f32 v18, v24, v25
	v_cvt_pk_bf16_f32 v19, v26, v27
	global_store_dwordx4 v[34:35], v[16:19], off nt
	s_nop 0
	s_waitcnt vmcnt(7)
	v_cvt_f32_u32_e32 v16, v197
	v_cvt_f32_u32_e32 v18, v196
	v_add_u32_e32 v17, 0xb0, v144
	v_fmamk_f32 v16, v18, 0x2f800000, v16
	v_fmamk_f32 v16, v16, 0x3a800000, v158
	v_rsq_f32_e32 v16, v16
	v_mad_i64_i32 v[18:19], s[38:39], v17, s51, v[146:147]
	v_lshl_add_u64 v[18:19], v[18:19], 0, v[148:149]
	v_mul_f32_e32 v196, 0xbfb8aa3b, v16
	v_mul_f32_e32 v197, v16, v16
	v_pk_mul_f32 v[16:17], v[12:13], v[196:197] op_sel_hi:[1,0]
	v_pk_mul_f32 v[20:21], v[14:15], v[196:197] op_sel_hi:[1,0]
	v_pk_mul_f32 v[22:23], v[8:9], v[196:197] op_sel_hi:[1,0]
	v_pk_mul_f32 v[24:25], v[10:11], v[196:197] op_sel_hi:[1,0]
	v_pk_mul_f32 v[4:5], v[4:5], v[12:13]
	v_pk_mul_f32 v[6:7], v[6:7], v[14:15]
	v_pk_mul_f32 v[8:9], v[0:1], v[8:9]
	v_pk_mul_f32 v[10:11], v[2:3], v[10:11]
	v_exp_f32_e32 v16, v16
	v_exp_f32_e32 v17, v17
	v_exp_f32_e32 v20, v20
	v_exp_f32_e32 v21, v21
	v_exp_f32_e32 v22, v22
	v_exp_f32_e32 v23, v23
	v_exp_f32_e32 v24, v24
	v_exp_f32_e32 v25, v25
	v_pk_mul_f32 v[4:5], v[4:5], v[196:197] op_sel:[0,1] op_sel_hi:[1,1]
	v_pk_mul_f32 v[6:7], v[6:7], v[196:197] op_sel:[0,1] op_sel_hi:[1,1]
	v_pk_mul_f32 v[8:9], v[8:9], v[196:197] op_sel:[0,1] op_sel_hi:[1,1]
	v_pk_mul_f32 v[10:11], v[10:11], v[196:197] op_sel:[0,1] op_sel_hi:[1,1]
	v_pk_add_f32 v[16:17], v[16:17], 1.0 op_sel_hi:[1,0]
	v_pk_add_f32 v[20:21], v[20:21], 1.0 op_sel_hi:[1,0]
	v_pk_add_f32 v[22:23], v[22:23], 1.0 op_sel_hi:[1,0]
	v_pk_add_f32 v[24:25], v[24:25], 1.0 op_sel_hi:[1,0]
	v_rcp_f32_e32 v16, v16
	v_rcp_f32_e32 v17, v17
	v_rcp_f32_e32 v20, v20
	v_rcp_f32_e32 v21, v21
	v_rcp_f32_e32 v22, v22
	v_rcp_f32_e32 v23, v23
	v_rcp_f32_e32 v24, v24
	v_rcp_f32_e32 v25, v25
	v_pk_mul_f32 v[4:5], v[4:5], v[16:17]
	v_pk_mul_f32 v[6:7], v[6:7], v[20:21]
	v_pk_mul_f32 v[8:9], v[8:9], v[22:23]
	v_pk_mul_f32 v[10:11], v[10:11], v[24:25]
	v_cvt_pk_bf16_f32 v0, v4, v5
	v_cvt_pk_bf16_f32 v1, v6, v7
	v_cvt_pk_bf16_f32 v2, v8, v9
	v_cvt_pk_bf16_f32 v3, v10, v11
	global_store_dwordx4 v[18:19], v[0:3], off nt
	s_cbranch_vccnz .LBB0_1896
	s_andn2_b64 vcc, exec, s[6:7]
	s_cbranch_vccnz .LBB0_1895
	s_barrier
	s_branch .LBB0_1895
